# v21 + nt hint on the converted-weight stores of phase 0
# speedup vs baseline: 1.0142x; 1.0082x over previous
.LBB0_23:
	s_cmpk_gt_i32 s52, 0x5ff
	s_mov_b64 s[10:11], -1
	s_cbranch_scc0 .LBB0_65
	s_cmpk_gt_u32 s52, 0x7ff
	s_cbranch_scc0 .LBB0_62
	s_cmpk_gt_u32 s52, 0x9ff
	s_cbranch_scc0 .LBB0_55
	s_cmpk_gt_u32 s52, 0xaff
	s_cbranch_scc0 .LBB0_52
	s_cmpk_gt_u32 s52, 0xbff
	s_cbranch_scc0 .LBB0_49
	s_cmpk_gt_u32 s52, 0x117f
	s_cbranch_scc0 .LBB0_42
	s_cmpk_gt_u32 s52, 0x143f
	s_cbranch_scc0 .LBB0_39
	s_cmpk_gt_u32 s52, 0x4c3f
	s_cbranch_scc0 .LBB0_32
	s_add_i32 s0, s52, 0xb3c0
	s_bfe_u32 s10, s0, 0x90007
	s_mulk_i32 s10, 0x2493
	s_lshr_b32 s12, s10, 16
	s_mul_i32 s10, s12, 0x380
	s_sub_i32 s0, s0, s10
	s_and_b32 s10, s0, 0xffff
	s_lshl_b32 s0, s10, 2
	s_lshl_b32 s10, s10, 6
	v_readlane_b32 s56, v234, 23
	s_and_b32 s0, s0, 0xfc0
	s_and_b32 s13, s10, 0x3c0
	s_mul_i32 s10, s12, 0xe00000
	v_readlane_b32 s68, v234, 35
	v_readlane_b32 s69, v234, 36
	s_add_u32 s10, s68, s10
	s_addc_u32 s11, s69, 0
	s_lshl_b32 s14, s0, 12
	s_add_u32 s10, s10, s14
	s_addc_u32 s11, s11, 0
	s_lshl_b32 s14, s13, 2
	s_add_u32 s10, s10, s14
	s_addc_u32 s11, s11, 0
	v_lshl_add_u64 v[78:79], s[10:11], 0, v[66:67]
	v_lshlrev_b32_e32 v4, 2, v2
	v_lshl_add_u64 v[134:135], v[78:79], 0, v[4:5]
	v_add_co_u32_e32 v82, vcc, s21, v134
	global_load_dwordx4 v[78:81], v[134:135], off nt
	s_nop 0
	v_addc_co_u32_e32 v83, vcc, 0, v135, vcc
	v_add_co_u32_e32 v86, vcc, s24, v134
	global_load_dwordx4 v[82:85], v[82:83], off nt
	s_nop 0
	v_addc_co_u32_e32 v87, vcc, 0, v135, vcc
	v_add_co_u32_e32 v90, vcc, s25, v134
	global_load_dwordx4 v[86:89], v[86:87], off nt
	s_nop 0
	v_addc_co_u32_e32 v91, vcc, 0, v135, vcc
	v_add_co_u32_e32 v94, vcc, s26, v134
	global_load_dwordx4 v[90:93], v[90:91], off nt
	s_nop 0
	v_addc_co_u32_e32 v95, vcc, 0, v135, vcc
	v_add_co_u32_e32 v98, vcc, s27, v134
	global_load_dwordx4 v[94:97], v[94:95], off nt
	s_nop 0
	v_addc_co_u32_e32 v99, vcc, 0, v135, vcc
	v_add_co_u32_e32 v102, vcc, s28, v134
	global_load_dwordx4 v[98:101], v[98:99], off nt
	s_nop 0
	v_addc_co_u32_e32 v103, vcc, 0, v135, vcc
	v_add_co_u32_e32 v106, vcc, s29, v134
	global_load_dwordx4 v[102:105], v[102:103], off nt
	s_nop 0
	v_addc_co_u32_e32 v107, vcc, 0, v135, vcc
	v_add_co_u32_e32 v110, vcc, s30, v134
	global_load_dwordx4 v[106:109], v[106:107], off nt
	s_nop 0
	v_addc_co_u32_e32 v111, vcc, 0, v135, vcc
	v_add_co_u32_e32 v114, vcc, s31, v134
	global_load_dwordx4 v[110:113], v[110:111], off nt
	s_nop 0
	v_addc_co_u32_e32 v115, vcc, 0, v135, vcc
	v_add_co_u32_e32 v118, vcc, s34, v134
	global_load_dwordx4 v[114:117], v[114:115], off nt
	s_nop 0
	v_addc_co_u32_e32 v119, vcc, 0, v135, vcc
	v_add_co_u32_e32 v122, vcc, s35, v134
	v_add_u32_e32 v4, 0x410, v1
	s_nop 0
	v_addc_co_u32_e32 v123, vcc, 0, v135, vcc
	global_load_dwordx4 v[118:121], v[118:119], off nt
	s_nop 0
	global_load_dwordx4 v[122:125], v[122:123], off nt
	v_add_co_u32_e32 v126, vcc, s36, v134
	s_lshl_b32 s10, s12, 10
	s_nop 0
	v_addc_co_u32_e32 v127, vcc, 0, v135, vcc
	v_add_co_u32_e32 v130, vcc, s37, v134
	s_or_b32 s10, s10, s13
	s_nop 0
	v_addc_co_u32_e32 v131, vcc, 0, v135, vcc
	global_load_dwordx4 v[126:129], v[126:127], off nt
	s_nop 0
	global_load_dwordx4 v[130:133], v[130:131], off nt
	v_add_co_u32_e32 v136, vcc, s38, v134
	s_mulk_i32 s10, 0xe00
	s_nop 0
	v_addc_co_u32_e32 v137, vcc, 0, v135, vcc
	v_add_co_u32_e32 v138, vcc, s39, v134
	v_readlane_b32 s11, v234, 40
	s_nop 0
	v_addc_co_u32_e32 v139, vcc, 0, v135, vcc
	global_load_dwordx4 v[134:137], v[136:137], off nt
	s_nop 0
	global_load_dwordx4 v[138:141], v[138:139], off nt
	s_add_u32 s10, s11, s10
	v_readlane_b32 s11, v234, 41
	s_addc_u32 s11, s11, 0
	s_add_u32 s10, s10, s0
	s_waitcnt vmcnt(15)
	v_pk_mul_f32 v[78:79], v[78:79], s[4:5] op_sel_hi:[1,0]
	ds_write2_b32 v1, v78, v79 offset1:1
	v_pk_mul_f32 v[78:79], v[80:81], s[4:5] op_sel_hi:[1,0]
	ds_write2_b32 v1, v78, v79 offset0:2 offset1:3
	s_addc_u32 s11, s11, 0
	s_waitcnt vmcnt(14)
	v_pk_mul_f32 v[78:79], v[82:83], s[4:5] op_sel_hi:[1,0]
	ds_write2_b32 v4, v78, v79 offset1:1
	v_pk_mul_f32 v[78:79], v[84:85], s[4:5] op_sel_hi:[1,0]
	v_add_u32_e32 v4, 0x418, v1
	ds_write2_b32 v4, v78, v79 offset1:1
	s_waitcnt vmcnt(13)
	v_pk_mul_f32 v[78:79], v[86:87], s[4:5] op_sel_hi:[1,0]
	v_add_u32_e32 v4, 0x820, v1
	ds_write2_b32 v4, v78, v79 offset1:1
	v_pk_mul_f32 v[78:79], v[88:89], s[4:5] op_sel_hi:[1,0]
	v_add_u32_e32 v4, 0x828, v1
	ds_write2_b32 v4, v78, v79 offset1:1
	s_waitcnt vmcnt(12)
	v_pk_mul_f32 v[78:79], v[90:91], s[4:5] op_sel_hi:[1,0]
	v_add_u32_e32 v4, 0xc30, v1
	ds_write2_b32 v4, v78, v79 offset1:1
	v_pk_mul_f32 v[78:79], v[92:93], s[4:5] op_sel_hi:[1,0]
	v_add_u32_e32 v4, 0xc38, v1
	ds_write2_b32 v4, v78, v79 offset1:1
	s_waitcnt vmcnt(11)
	v_pk_mul_f32 v[78:79], v[94:95], s[4:5] op_sel_hi:[1,0]
	v_add_u32_e32 v4, 0x1040, v1
	ds_write2_b32 v4, v78, v79 offset1:1
	v_pk_mul_f32 v[78:79], v[96:97], s[4:5] op_sel_hi:[1,0]
	v_add_u32_e32 v4, 0x1048, v1
	ds_write2_b32 v4, v78, v79 offset1:1
	s_waitcnt vmcnt(10)
	v_pk_mul_f32 v[78:79], v[98:99], s[4:5] op_sel_hi:[1,0]
	v_add_u32_e32 v4, 0x1450, v1
	ds_write2_b32 v4, v78, v79 offset1:1
	v_pk_mul_f32 v[78:79], v[100:101], s[4:5] op_sel_hi:[1,0]
	v_add_u32_e32 v4, 0x1458, v1
	ds_write2_b32 v4, v78, v79 offset1:1
	s_waitcnt vmcnt(9)
	v_pk_mul_f32 v[78:79], v[102:103], s[4:5] op_sel_hi:[1,0]
	v_add_u32_e32 v4, 0x1860, v1
	ds_write2_b32 v4, v78, v79 offset1:1
	v_pk_mul_f32 v[78:79], v[104:105], s[4:5] op_sel_hi:[1,0]
	v_add_u32_e32 v4, 0x1868, v1
	ds_write2_b32 v4, v78, v79 offset1:1
	s_waitcnt vmcnt(8)
	v_pk_mul_f32 v[78:79], v[106:107], s[4:5] op_sel_hi:[1,0]
	v_add_u32_e32 v4, 0x1c70, v1
	ds_write2_b32 v4, v78, v79 offset1:1
	v_pk_mul_f32 v[78:79], v[108:109], s[4:5] op_sel_hi:[1,0]
	v_add_u32_e32 v4, 0x1c78, v1
	ds_write2_b32 v4, v78, v79 offset1:1
	s_waitcnt vmcnt(7)
	v_pk_mul_f32 v[78:79], v[110:111], s[4:5] op_sel_hi:[1,0]
	v_add_u32_e32 v4, 0x2080, v1
	ds_write2_b32 v4, v78, v79 offset1:1
	v_pk_mul_f32 v[78:79], v[112:113], s[4:5] op_sel_hi:[1,0]
	v_add_u32_e32 v4, 0x2088, v1
	ds_write2_b32 v4, v78, v79 offset1:1
	s_waitcnt vmcnt(6)
	v_pk_mul_f32 v[78:79], v[114:115], s[4:5] op_sel_hi:[1,0]
	v_add_u32_e32 v4, 0x2490, v1
	ds_write2_b32 v4, v78, v79 offset1:1
	v_pk_mul_f32 v[78:79], v[116:117], s[4:5] op_sel_hi:[1,0]
	v_add_u32_e32 v4, 0x2498, v1
	ds_write2_b32 v4, v78, v79 offset1:1
	s_waitcnt vmcnt(5)
	v_pk_mul_f32 v[78:79], v[118:119], s[4:5] op_sel_hi:[1,0]
	v_add_u32_e32 v4, 0x28a0, v1
	ds_write2_b32 v4, v78, v79 offset1:1
	v_pk_mul_f32 v[78:79], v[120:121], s[4:5] op_sel_hi:[1,0]
	v_add_u32_e32 v4, 0x28a8, v1
	ds_write2_b32 v4, v78, v79 offset1:1
	s_waitcnt vmcnt(4)
	v_pk_mul_f32 v[78:79], v[122:123], s[4:5] op_sel_hi:[1,0]
	v_add_u32_e32 v4, 0x2cb0, v1
	ds_write2_b32 v4, v78, v79 offset1:1
	v_pk_mul_f32 v[78:79], v[124:125], s[4:5] op_sel_hi:[1,0]
	v_add_u32_e32 v4, 0x2cb8, v1
	ds_write2_b32 v4, v78, v79 offset1:1
	s_waitcnt vmcnt(3)
	v_pk_mul_f32 v[78:79], v[126:127], s[4:5] op_sel_hi:[1,0]
	v_add_u32_e32 v4, 0x30c0, v1
	ds_write2_b32 v4, v78, v79 offset1:1
	v_pk_mul_f32 v[78:79], v[128:129], s[4:5] op_sel_hi:[1,0]
	v_add_u32_e32 v4, 0x30c8, v1
	ds_write2_b32 v4, v78, v79 offset1:1
	s_waitcnt vmcnt(2)
	v_pk_mul_f32 v[78:79], v[130:131], s[4:5] op_sel_hi:[1,0]
	v_add_u32_e32 v4, 0x34d0, v1
	ds_write2_b32 v4, v78, v79 offset1:1
	v_pk_mul_f32 v[78:79], v[132:133], s[4:5] op_sel_hi:[1,0]
	v_add_u32_e32 v4, 0x34d8, v1
	ds_write2_b32 v4, v78, v79 offset1:1
	s_waitcnt vmcnt(1)
	v_pk_mul_f32 v[78:79], v[134:135], s[4:5] op_sel_hi:[1,0]
	v_add_u32_e32 v4, 0x38e0, v1
	ds_write2_b32 v4, v78, v79 offset1:1
	v_pk_mul_f32 v[78:79], v[136:137], s[4:5] op_sel_hi:[1,0]
	v_add_u32_e32 v4, 0x38e8, v1
	ds_write2_b32 v4, v78, v79 offset1:1
	s_waitcnt vmcnt(0)
	v_pk_mul_f32 v[78:79], v[138:139], s[4:5] op_sel_hi:[1,0]
	v_add_u32_e32 v4, 0x3cf0, v1
	ds_write2_b32 v4, v78, v79 offset1:1
	v_pk_mul_f32 v[78:79], v[140:141], s[4:5] op_sel_hi:[1,0]
	v_add_u32_e32 v4, 0x3cf8, v1
	ds_write2_b32 v4, v78, v79 offset1:1
	s_waitcnt lgkmcnt(0)
	ds_read2_b32 v[82:83], v3 offset1:16
	ds_read2_b32 v[84:85], v3 offset0:65 offset1:81
	v_mov_b32_e32 v78, v5
	ds_read2_b32 v[88:89], v3 offset0:130 offset1:146
	ds_read2_b32 v[90:91], v3 offset0:195 offset1:211
	v_add_u32_e32 v118, 0xc00, v3
	s_waitcnt lgkmcnt(3)
	v_med3_f32 v4, v82, s40, v76
	s_waitcnt lgkmcnt(2)
	v_med3_f32 v77, v84, s40, v76
	v_cvt_pk_fp8_f32 v78, v4, v77
	v_add_u32_e32 v4, 0x400, v3
	ds_read2_b32 v[92:93], v4 offset0:4 offset1:20
	ds_read2_b32 v[94:95], v4 offset0:69 offset1:85
	s_waitcnt lgkmcnt(3)
	v_med3_f32 v77, v88, s40, v76
	s_waitcnt lgkmcnt(2)
	v_med3_f32 v79, v90, s40, v76
	v_cvt_pk_fp8_f32 v78, v77, v79 op_sel:[0,0,1]
	s_waitcnt lgkmcnt(1)
	v_med3_f32 v77, v92, s40, v76
	s_waitcnt lgkmcnt(0)
	v_med3_f32 v80, v94, s40, v76
	v_mov_b32_e32 v79, v5
	v_cvt_pk_fp8_f32 v79, v77, v80
	ds_read2_b32 v[96:97], v4 offset0:134 offset1:150
	ds_read2_b32 v[98:99], v4 offset0:199 offset1:215
	v_add_u32_e32 v77, 0x800, v3
	ds_read2_b32 v[100:101], v77 offset0:8 offset1:24
	ds_read2_b32 v[102:103], v77 offset0:73 offset1:89
	ds_read2_b32 v[104:105], v77 offset0:138 offset1:154
	ds_read2_b32 v[106:107], v77 offset0:203 offset1:219
	ds_read2_b32 v[108:109], v118 offset0:12 offset1:28
	ds_read2_b32 v[110:111], v118 offset0:77 offset1:93
	s_waitcnt lgkmcnt(7)
	v_med3_f32 v80, v96, s40, v76
	s_waitcnt lgkmcnt(6)
	v_med3_f32 v81, v98, s40, v76
	v_cvt_pk_fp8_f32 v79, v80, v81 op_sel:[0,0,1]
	s_waitcnt lgkmcnt(5)
	v_med3_f32 v81, v100, s40, v76
	s_waitcnt lgkmcnt(4)
	v_med3_f32 v82, v102, s40, v76
	v_mov_b32_e32 v80, v5
	ds_read2_b32 v[112:113], v118 offset0:142 offset1:158
	ds_read2_b32 v[114:115], v118 offset0:207 offset1:223
	v_cvt_pk_fp8_f32 v80, v81, v82
	s_waitcnt lgkmcnt(3)
	v_med3_f32 v88, v108, s40, v76
	s_waitcnt lgkmcnt(2)
	v_med3_f32 v90, v110, s40, v76
	v_mov_b32_e32 v81, v5
	v_cvt_pk_fp8_f32 v81, v88, v90
	v_med3_f32 v82, v104, s40, v76
	v_med3_f32 v84, v106, s40, v76
	v_cvt_pk_fp8_f32 v80, v82, v84 op_sel:[0,0,1]
	s_waitcnt lgkmcnt(1)
	v_med3_f32 v82, v112, s40, v76
	s_waitcnt lgkmcnt(0)
	v_med3_f32 v84, v114, s40, v76
	v_cvt_pk_fp8_f32 v81, v82, v84 op_sel:[0,0,1]
	v_med3_f32 v83, v83, s40, v76
	v_med3_f32 v84, v85, s40, v76
	v_mov_b32_e32 v82, v5
	v_cvt_pk_fp8_f32 v82, v83, v84
	v_med3_f32 v84, v89, s40, v76
	v_med3_f32 v88, v93, s40, v76
	v_med3_f32 v89, v95, s40, v76
	v_mov_b32_e32 v83, v5
	v_cvt_pk_fp8_f32 v83, v88, v89
	v_med3_f32 v85, v91, s40, v76
	v_cvt_pk_fp8_f32 v82, v84, v85 op_sel:[0,0,1]
	v_med3_f32 v84, v97, s40, v76
	v_med3_f32 v85, v99, s40, v76
	v_cvt_pk_fp8_f32 v83, v84, v85 op_sel:[0,0,1]
	v_med3_f32 v85, v101, s40, v76
	v_med3_f32 v88, v103, s40, v76
	v_mov_b32_e32 v84, v5
	v_cvt_pk_fp8_f32 v84, v85, v88
	v_med3_f32 v90, v109, s40, v76
	v_med3_f32 v91, v111, s40, v76
	v_mov_b32_e32 v85, v5
	v_cvt_pk_fp8_f32 v85, v90, v91
	v_med3_f32 v88, v105, s40, v76
	v_med3_f32 v89, v107, s40, v76
	v_cvt_pk_fp8_f32 v84, v88, v89 op_sel:[0,0,1]
	v_med3_f32 v88, v113, s40, v76
	v_med3_f32 v89, v115, s40, v76
	v_cvt_pk_fp8_f32 v85, v88, v89 op_sel:[0,0,1]
	v_lshl_add_u64 v[86:87], s[10:11], 0, v[6:7]
	ds_read2_b32 v[88:89], v3 offset0:32 offset1:48
	ds_read2_b32 v[90:91], v3 offset0:97 offset1:113
	v_lshl_add_u64 v[116:117], v[86:87], 0, v[8:9]
	global_store_dwordx4 v[116:117], v[78:81], off nt
	v_readlane_b32 s57, v234, 24
	v_readlane_b32 s58, v234, 25
	v_lshl_add_u64 v[78:79], v[86:87], 0, v[10:11]
	global_store_dwordx4 v[78:79], v[82:85], off nt
	ds_read2_b32 v[82:83], v3 offset0:162 offset1:178
	ds_read2_b32 v[84:85], v3 offset0:227 offset1:243
	s_waitcnt lgkmcnt(3)
	v_med3_f32 v79, v88, s40, v76
	s_waitcnt lgkmcnt(2)
	v_med3_f32 v80, v90, s40, v76
	v_mov_b32_e32 v78, v5
	ds_read2_b32 v[92:93], v4 offset0:36 offset1:52
	ds_read2_b32 v[94:95], v4 offset0:101 offset1:117
	v_cvt_pk_fp8_f32 v78, v79, v80
	s_waitcnt lgkmcnt(3)
	v_med3_f32 v79, v82, s40, v76
	s_waitcnt lgkmcnt(2)
	v_med3_f32 v80, v84, s40, v76
	ds_read2_b32 v[96:97], v4 offset0:166 offset1:182
	ds_read2_b32 v[98:99], v4 offset0:231 offset1:247
	v_cvt_pk_fp8_f32 v78, v79, v80 op_sel:[0,0,1]
	s_waitcnt lgkmcnt(3)
	v_med3_f32 v80, v92, s40, v76
	s_waitcnt lgkmcnt(2)
	v_med3_f32 v81, v94, s40, v76
	v_mov_b32_e32 v79, v5
	ds_read2_b32 v[100:101], v77 offset0:40 offset1:56
	ds_read2_b32 v[102:103], v77 offset0:105 offset1:121
	v_cvt_pk_fp8_f32 v79, v80, v81
	ds_read2_b32 v[104:105], v77 offset0:170 offset1:186
	ds_read2_b32 v[106:107], v77 offset0:235 offset1:251
	ds_read2_b32 v[108:109], v118 offset0:44 offset1:60
	ds_read2_b32 v[110:111], v118 offset0:109 offset1:125
	s_waitcnt lgkmcnt(7)
	v_med3_f32 v4, v96, s40, v76
	s_waitcnt lgkmcnt(6)
	v_med3_f32 v80, v98, s40, v76
	v_cvt_pk_fp8_f32 v79, v4, v80 op_sel:[0,0,1]
	s_waitcnt lgkmcnt(5)
	v_med3_f32 v4, v100, s40, v76
	s_waitcnt lgkmcnt(4)
	v_med3_f32 v81, v102, s40, v76
	v_mov_b32_e32 v80, v5
	ds_read2_b32 v[112:113], v118 offset0:174 offset1:190
	ds_read2_b32 v[114:115], v118 offset0:239 offset1:255
	v_cvt_pk_fp8_f32 v80, v4, v81
	s_waitcnt lgkmcnt(3)
	v_med3_f32 v82, v108, s40, v76
	s_waitcnt lgkmcnt(2)
	v_med3_f32 v84, v110, s40, v76
	v_mov_b32_e32 v81, v5
	v_cvt_pk_fp8_f32 v81, v82, v84
	v_med3_f32 v4, v104, s40, v76
	v_med3_f32 v77, v106, s40, v76
	v_cvt_pk_fp8_f32 v80, v4, v77 op_sel:[0,0,1]
	s_waitcnt lgkmcnt(1)
	v_med3_f32 v4, v112, s40, v76
	s_waitcnt lgkmcnt(0)
	v_med3_f32 v77, v114, s40, v76
	v_cvt_pk_fp8_f32 v81, v4, v77 op_sel:[0,0,1]
	v_med3_f32 v4, v89, s40, v76
	v_med3_f32 v77, v91, s40, v76
	v_mov_b32_e32 v82, v5
	v_cvt_pk_fp8_f32 v82, v4, v77
	v_med3_f32 v4, v83, s40, v76
	v_med3_f32 v77, v85, s40, v76
	v_med3_f32 v84, v93, s40, v76
	v_med3_f32 v85, v95, s40, v76
	v_mov_b32_e32 v83, v5
	v_cvt_pk_fp8_f32 v83, v84, v85
	v_cvt_pk_fp8_f32 v82, v4, v77 op_sel:[0,0,1]
	v_med3_f32 v4, v97, s40, v76
	v_med3_f32 v77, v99, s40, v76
	v_cvt_pk_fp8_f32 v83, v4, v77 op_sel:[0,0,1]
	v_med3_f32 v4, v101, s40, v76
	v_med3_f32 v77, v103, s40, v76
	v_mov_b32_e32 v84, v5
	v_cvt_pk_fp8_f32 v84, v4, v77
	v_med3_f32 v88, v109, s40, v76
	v_med3_f32 v89, v111, s40, v76
	v_mov_b32_e32 v85, v5
	v_cvt_pk_fp8_f32 v85, v88, v89
	v_med3_f32 v4, v105, s40, v76
	v_med3_f32 v77, v107, s40, v76
	v_cvt_pk_fp8_f32 v84, v4, v77 op_sel:[0,0,1]
	v_med3_f32 v4, v113, s40, v76
	v_med3_f32 v77, v115, s40, v76
	v_cvt_pk_fp8_f32 v85, v4, v77 op_sel:[0,0,1]
	v_lshl_add_u64 v[88:89], v[86:87], 0, v[12:13]
	global_store_dwordx4 v[88:89], v[78:81], off nt
	v_readlane_b32 s59, v234, 26
	v_readlane_b32 s60, v234, 27
	v_lshl_add_u64 v[78:79], v[86:87], 0, v[14:15]
	global_store_dwordx4 v[78:79], v[82:85], off nt
	s_waitcnt lgkmcnt(0)
	v_readlane_b32 s61, v234, 28
	v_readlane_b32 s62, v234, 29
	v_readlane_b32 s63, v234, 30
	v_readlane_b32 s64, v234, 31
	v_readlane_b32 s65, v234, 32
	v_readlane_b32 s66, v234, 33
	v_readlane_b32 s67, v234, 34
	v_readlane_b32 s70, v234, 37
	v_readlane_b32 s71, v234, 38
	s_mov_b64 s[10:11], 0

.LBB0_37:
	v_readlane_b32 s56, v234, 23
	s_lshl_b32 s10, s13, 6
	s_mul_i32 s12, s12, 0x1c00000
	v_readlane_b32 s66, v234, 33
	v_readlane_b32 s67, v234, 34
	s_add_u32 s12, s66, s12
	s_addc_u32 s15, s67, 0
	s_and_b32 s10, s10, 0xffc0
	s_mul_i32 s13, s13, 0x1c0000
	s_add_u32 s12, s12, s13
	s_addc_u32 s13, s15, 0
	s_and_b32 s14, 0xffff, s14
	s_lshl_b32 s14, s14, 2
	s_add_u32 s12, s12, s14
	s_addc_u32 s13, s13, 0
	v_lshl_add_u64 v[78:79], s[12:13], 0, v[68:69]
	v_lshlrev_b32_e32 v4, 2, v2
	v_lshl_add_u64 v[134:135], v[78:79], 0, v[4:5]
	v_add_co_u32_e32 v82, vcc, s29, v134
	s_add_i32 s0, s11, s0
	s_nop 0
	v_addc_co_u32_e32 v83, vcc, 0, v135, vcc
	global_load_dwordx4 v[78:81], v[134:135], off nt
	s_nop 0
	global_load_dwordx4 v[82:85], v[82:83], off nt
	v_add_co_u32_e32 v86, vcc, s38, v134
	s_mov_b32 s11, 0x54000
	s_nop 0
	v_addc_co_u32_e32 v87, vcc, 0, v135, vcc
	v_add_co_u32_e32 v90, vcc, s11, v134
	s_mov_b32 s11, 0x8c000
	s_nop 0
	v_addc_co_u32_e32 v91, vcc, 0, v135, vcc
	global_load_dwordx4 v[86:89], v[86:87], off nt
	s_nop 0
	global_load_dwordx4 v[90:93], v[90:91], off nt
	v_add_co_u32_e32 v94, vcc, s41, v134
	s_lshl_b64 s[12:13], s[0:1], 10
	s_nop 0
	v_addc_co_u32_e32 v95, vcc, 0, v135, vcc
	v_add_co_u32_e32 v98, vcc, s11, v134
	s_add_u32 s0, s77, s12
	s_nop 0
	v_addc_co_u32_e32 v99, vcc, 0, v135, vcc
	global_load_dwordx4 v[94:97], v[94:95], off nt
	s_nop 0
	global_load_dwordx4 v[98:101], v[98:99], off nt
	v_add_co_u32_e32 v102, vcc, s42, v134
	s_mov_b32 s12, 0xc4000
	s_nop 0
	v_addc_co_u32_e32 v103, vcc, 0, v135, vcc
	v_add_co_u32_e32 v106, vcc, s12, v134
	s_mov_b32 s12, 0xe0000
	s_nop 0
	v_addc_co_u32_e32 v107, vcc, 0, v135, vcc
	global_load_dwordx4 v[102:105], v[102:103], off nt
	s_nop 0
	global_load_dwordx4 v[106:109], v[106:107], off nt
	v_add_co_u32_e32 v110, vcc, s12, v134
	s_mov_b32 s12, 0xfc000
	s_nop 0
	v_addc_co_u32_e32 v111, vcc, 0, v135, vcc
	v_add_co_u32_e32 v114, vcc, s12, v134
	s_mov_b32 s12, 0x118000
	s_nop 0
	v_addc_co_u32_e32 v115, vcc, 0, v135, vcc
	global_load_dwordx4 v[110:113], v[110:111], off nt
	s_nop 0
	global_load_dwordx4 v[114:117], v[114:115], off nt
	v_add_co_u32_e32 v118, vcc, s12, v134
	s_mov_b32 s12, 0x16c000
	s_nop 0
	v_addc_co_u32_e32 v119, vcc, 0, v135, vcc
	v_add_co_u32_e32 v122, vcc, s43, v134
	v_add_u32_e32 v4, 0x410, v1
	s_nop 0
	v_addc_co_u32_e32 v123, vcc, 0, v135, vcc
	global_load_dwordx4 v[118:121], v[118:119], off nt
	s_nop 0
	global_load_dwordx4 v[122:125], v[122:123], off nt
	v_add_co_u32_e32 v126, vcc, s44, v134
	v_readlane_b32 s11, v234, 42
	s_nop 0
	v_addc_co_u32_e32 v127, vcc, 0, v135, vcc
	v_add_co_u32_e32 v130, vcc, s12, v134
	s_mov_b32 s12, 0x188000
	s_nop 0
	v_addc_co_u32_e32 v131, vcc, 0, v135, vcc
	global_load_dwordx4 v[126:129], v[126:127], off nt
	s_nop 0
	global_load_dwordx4 v[130:133], v[130:131], off nt
	v_add_co_u32_e32 v136, vcc, s12, v134
	s_mov_b32 s12, 0x1a4000
	s_nop 0
	v_addc_co_u32_e32 v137, vcc, 0, v135, vcc
	v_add_co_u32_e32 v138, vcc, s12, v134
	s_addc_u32 s11, s11, s13
	s_nop 0
	v_addc_co_u32_e32 v139, vcc, 0, v135, vcc
	global_load_dwordx4 v[134:137], v[136:137], off nt
	s_nop 0
	global_load_dwordx4 v[138:141], v[138:139], off nt
	s_add_u32 s10, s0, s10
	s_waitcnt vmcnt(15)
	v_pk_mul_f32 v[78:79], v[78:79], s[6:7] op_sel_hi:[1,0]
	ds_write2_b32 v1, v78, v79 offset1:1
	v_pk_mul_f32 v[78:79], v[80:81], s[6:7] op_sel_hi:[1,0]
	ds_write2_b32 v1, v78, v79 offset0:2 offset1:3
	s_waitcnt vmcnt(14)
	v_pk_mul_f32 v[78:79], v[82:83], s[6:7] op_sel_hi:[1,0]
	ds_write2_b32 v4, v78, v79 offset1:1
	v_pk_mul_f32 v[78:79], v[84:85], s[6:7] op_sel_hi:[1,0]
	v_add_u32_e32 v4, 0x418, v1
	ds_write2_b32 v4, v78, v79 offset1:1
	v_add_u32_e32 v4, 0x820, v1
	s_addc_u32 s11, s11, 0
	s_waitcnt vmcnt(13)
	v_pk_mul_f32 v[78:79], v[86:87], s[6:7] op_sel_hi:[1,0]
	ds_write2_b32 v4, v78, v79 offset1:1
	v_pk_mul_f32 v[78:79], v[88:89], s[6:7] op_sel_hi:[1,0]
	v_add_u32_e32 v4, 0x828, v1
	ds_write2_b32 v4, v78, v79 offset1:1
	s_waitcnt vmcnt(12)
	v_pk_mul_f32 v[78:79], v[90:91], s[6:7] op_sel_hi:[1,0]
	v_add_u32_e32 v4, 0xc30, v1
	ds_write2_b32 v4, v78, v79 offset1:1
	v_pk_mul_f32 v[78:79], v[92:93], s[6:7] op_sel_hi:[1,0]
	v_add_u32_e32 v4, 0xc38, v1
	ds_write2_b32 v4, v78, v79 offset1:1
	s_waitcnt vmcnt(11)
	v_pk_mul_f32 v[78:79], v[94:95], s[6:7] op_sel_hi:[1,0]
	v_add_u32_e32 v4, 0x1040, v1
	ds_write2_b32 v4, v78, v79 offset1:1
	v_pk_mul_f32 v[78:79], v[96:97], s[6:7] op_sel_hi:[1,0]
	v_add_u32_e32 v4, 0x1048, v1
	ds_write2_b32 v4, v78, v79 offset1:1
	s_waitcnt vmcnt(10)
	v_pk_mul_f32 v[78:79], v[98:99], s[6:7] op_sel_hi:[1,0]
	v_add_u32_e32 v4, 0x1450, v1
	ds_write2_b32 v4, v78, v79 offset1:1
	v_pk_mul_f32 v[78:79], v[100:101], s[6:7] op_sel_hi:[1,0]
	v_add_u32_e32 v4, 0x1458, v1
	ds_write2_b32 v4, v78, v79 offset1:1
	s_waitcnt vmcnt(9)
	v_pk_mul_f32 v[78:79], v[102:103], s[6:7] op_sel_hi:[1,0]
	v_add_u32_e32 v4, 0x1860, v1
	ds_write2_b32 v4, v78, v79 offset1:1
	v_pk_mul_f32 v[78:79], v[104:105], s[6:7] op_sel_hi:[1,0]
	v_add_u32_e32 v4, 0x1868, v1
	ds_write2_b32 v4, v78, v79 offset1:1
	s_waitcnt vmcnt(8)
	v_pk_mul_f32 v[78:79], v[106:107], s[6:7] op_sel_hi:[1,0]
	v_add_u32_e32 v4, 0x1c70, v1
	ds_write2_b32 v4, v78, v79 offset1:1
	v_pk_mul_f32 v[78:79], v[108:109], s[6:7] op_sel_hi:[1,0]
	v_add_u32_e32 v4, 0x1c78, v1
	ds_write2_b32 v4, v78, v79 offset1:1
	s_waitcnt vmcnt(7)
	v_pk_mul_f32 v[78:79], v[110:111], s[6:7] op_sel_hi:[1,0]
	v_add_u32_e32 v4, 0x2080, v1
	ds_write2_b32 v4, v78, v79 offset1:1
	v_pk_mul_f32 v[78:79], v[112:113], s[6:7] op_sel_hi:[1,0]
	v_add_u32_e32 v4, 0x2088, v1
	ds_write2_b32 v4, v78, v79 offset1:1
	s_waitcnt vmcnt(6)
	v_pk_mul_f32 v[78:79], v[114:115], s[6:7] op_sel_hi:[1,0]
	v_add_u32_e32 v4, 0x2490, v1
	ds_write2_b32 v4, v78, v79 offset1:1
	v_pk_mul_f32 v[78:79], v[116:117], s[6:7] op_sel_hi:[1,0]
	v_add_u32_e32 v4, 0x2498, v1
	ds_write2_b32 v4, v78, v79 offset1:1
	s_waitcnt vmcnt(5)
	v_pk_mul_f32 v[78:79], v[118:119], s[6:7] op_sel_hi:[1,0]
	v_add_u32_e32 v4, 0x28a0, v1
	ds_write2_b32 v4, v78, v79 offset1:1
	v_pk_mul_f32 v[78:79], v[120:121], s[6:7] op_sel_hi:[1,0]
	v_add_u32_e32 v4, 0x28a8, v1
	ds_write2_b32 v4, v78, v79 offset1:1
	s_waitcnt vmcnt(4)
	v_pk_mul_f32 v[78:79], v[122:123], s[6:7] op_sel_hi:[1,0]
	v_add_u32_e32 v4, 0x2cb0, v1
	ds_write2_b32 v4, v78, v79 offset1:1
	v_pk_mul_f32 v[78:79], v[124:125], s[6:7] op_sel_hi:[1,0]
	v_add_u32_e32 v4, 0x2cb8, v1
	ds_write2_b32 v4, v78, v79 offset1:1
	s_waitcnt vmcnt(3)
	v_pk_mul_f32 v[78:79], v[126:127], s[6:7] op_sel_hi:[1,0]
	v_add_u32_e32 v4, 0x30c0, v1
	ds_write2_b32 v4, v78, v79 offset1:1
	v_pk_mul_f32 v[78:79], v[128:129], s[6:7] op_sel_hi:[1,0]
	v_add_u32_e32 v4, 0x30c8, v1
	ds_write2_b32 v4, v78, v79 offset1:1
	s_waitcnt vmcnt(2)
	v_pk_mul_f32 v[78:79], v[130:131], s[6:7] op_sel_hi:[1,0]
	v_add_u32_e32 v4, 0x34d0, v1
	ds_write2_b32 v4, v78, v79 offset1:1
	v_pk_mul_f32 v[78:79], v[132:133], s[6:7] op_sel_hi:[1,0]
	v_add_u32_e32 v4, 0x34d8, v1
	ds_write2_b32 v4, v78, v79 offset1:1
	s_waitcnt vmcnt(1)
	v_pk_mul_f32 v[78:79], v[134:135], s[6:7] op_sel_hi:[1,0]
	v_add_u32_e32 v4, 0x38e0, v1
	ds_write2_b32 v4, v78, v79 offset1:1
	v_pk_mul_f32 v[78:79], v[136:137], s[6:7] op_sel_hi:[1,0]
	v_add_u32_e32 v4, 0x38e8, v1
	ds_write2_b32 v4, v78, v79 offset1:1
	s_waitcnt vmcnt(0)
	v_pk_mul_f32 v[78:79], v[138:139], s[6:7] op_sel_hi:[1,0]
	v_add_u32_e32 v4, 0x3cf0, v1
	ds_write2_b32 v4, v78, v79 offset1:1
	v_pk_mul_f32 v[78:79], v[140:141], s[6:7] op_sel_hi:[1,0]
	v_add_u32_e32 v4, 0x3cf8, v1
	ds_write2_b32 v4, v78, v79 offset1:1
	s_waitcnt lgkmcnt(0)
	ds_read2_b32 v[82:83], v3 offset1:16
	ds_read2_b32 v[84:85], v3 offset0:65 offset1:81
	v_mov_b32_e32 v78, v5
	ds_read2_b32 v[88:89], v3 offset0:130 offset1:146
	ds_read2_b32 v[90:91], v3 offset0:195 offset1:211
	v_add_u32_e32 v118, 0xc00, v3
	s_waitcnt lgkmcnt(3)
	v_med3_f32 v4, v82, s40, v76
	s_waitcnt lgkmcnt(2)
	v_med3_f32 v77, v84, s40, v76
	v_cvt_pk_fp8_f32 v78, v4, v77
	v_add_u32_e32 v4, 0x400, v3
	ds_read2_b32 v[92:93], v4 offset0:4 offset1:20
	ds_read2_b32 v[94:95], v4 offset0:69 offset1:85
	s_waitcnt lgkmcnt(3)
	v_med3_f32 v77, v88, s40, v76
	s_waitcnt lgkmcnt(2)
	v_med3_f32 v79, v90, s40, v76
	v_cvt_pk_fp8_f32 v78, v77, v79 op_sel:[0,0,1]
	s_waitcnt lgkmcnt(1)
	v_med3_f32 v77, v92, s40, v76
	s_waitcnt lgkmcnt(0)
	v_med3_f32 v80, v94, s40, v76
	v_mov_b32_e32 v79, v5
	v_cvt_pk_fp8_f32 v79, v77, v80
	ds_read2_b32 v[96:97], v4 offset0:134 offset1:150
	ds_read2_b32 v[98:99], v4 offset0:199 offset1:215
	v_add_u32_e32 v77, 0x800, v3
	ds_read2_b32 v[100:101], v77 offset0:8 offset1:24
	ds_read2_b32 v[102:103], v77 offset0:73 offset1:89
	ds_read2_b32 v[104:105], v77 offset0:138 offset1:154
	ds_read2_b32 v[106:107], v77 offset0:203 offset1:219
	ds_read2_b32 v[108:109], v118 offset0:12 offset1:28
	ds_read2_b32 v[110:111], v118 offset0:77 offset1:93
	s_waitcnt lgkmcnt(7)
	v_med3_f32 v80, v96, s40, v76
	s_waitcnt lgkmcnt(6)
	v_med3_f32 v81, v98, s40, v76
	v_cvt_pk_fp8_f32 v79, v80, v81 op_sel:[0,0,1]
	s_waitcnt lgkmcnt(5)
	v_med3_f32 v81, v100, s40, v76
	s_waitcnt lgkmcnt(4)
	v_med3_f32 v82, v102, s40, v76
	v_mov_b32_e32 v80, v5
	ds_read2_b32 v[112:113], v118 offset0:142 offset1:158
	ds_read2_b32 v[114:115], v118 offset0:207 offset1:223
	v_cvt_pk_fp8_f32 v80, v81, v82
	s_waitcnt lgkmcnt(3)
	v_med3_f32 v88, v108, s40, v76
	s_waitcnt lgkmcnt(2)
	v_med3_f32 v90, v110, s40, v76
	v_mov_b32_e32 v81, v5
	v_cvt_pk_fp8_f32 v81, v88, v90
	v_med3_f32 v82, v104, s40, v76
	v_med3_f32 v84, v106, s40, v76
	v_cvt_pk_fp8_f32 v80, v82, v84 op_sel:[0,0,1]
	s_waitcnt lgkmcnt(1)
	v_med3_f32 v82, v112, s40, v76
	s_waitcnt lgkmcnt(0)
	v_med3_f32 v84, v114, s40, v76
	v_cvt_pk_fp8_f32 v81, v82, v84 op_sel:[0,0,1]
	v_med3_f32 v83, v83, s40, v76
	v_med3_f32 v84, v85, s40, v76
	v_mov_b32_e32 v82, v5
	v_cvt_pk_fp8_f32 v82, v83, v84
	v_med3_f32 v84, v89, s40, v76
	v_med3_f32 v88, v93, s40, v76
	v_med3_f32 v89, v95, s40, v76
	v_mov_b32_e32 v83, v5
	v_cvt_pk_fp8_f32 v83, v88, v89
	v_med3_f32 v85, v91, s40, v76
	v_cvt_pk_fp8_f32 v82, v84, v85 op_sel:[0,0,1]
	v_med3_f32 v84, v97, s40, v76
	v_med3_f32 v85, v99, s40, v76
	v_cvt_pk_fp8_f32 v83, v84, v85 op_sel:[0,0,1]
	v_med3_f32 v85, v101, s40, v76
	v_med3_f32 v88, v103, s40, v76
	v_mov_b32_e32 v84, v5
	v_cvt_pk_fp8_f32 v84, v85, v88
	v_med3_f32 v90, v109, s40, v76
	v_med3_f32 v91, v111, s40, v76
	v_mov_b32_e32 v85, v5
	v_cvt_pk_fp8_f32 v85, v90, v91
	v_med3_f32 v88, v105, s40, v76
	v_med3_f32 v89, v107, s40, v76
	v_cvt_pk_fp8_f32 v84, v88, v89 op_sel:[0,0,1]
	v_med3_f32 v88, v113, s40, v76
	v_med3_f32 v89, v115, s40, v76
	v_cvt_pk_fp8_f32 v85, v88, v89 op_sel:[0,0,1]
	v_lshl_add_u64 v[86:87], s[10:11], 0, v[6:7]
	ds_read2_b32 v[88:89], v3 offset0:32 offset1:48
	ds_read2_b32 v[90:91], v3 offset0:97 offset1:113
	v_lshl_add_u64 v[116:117], v[86:87], 0, v[16:17]
	global_store_dwordx4 v[116:117], v[78:81], off nt
	v_readlane_b32 s57, v234, 24
	v_readlane_b32 s58, v234, 25
	v_lshl_add_u64 v[78:79], v[86:87], 0, v[18:19]
	global_store_dwordx4 v[78:79], v[82:85], off nt
	ds_read2_b32 v[82:83], v3 offset0:162 offset1:178
	ds_read2_b32 v[84:85], v3 offset0:227 offset1:243
	s_waitcnt lgkmcnt(3)
	v_med3_f32 v79, v88, s40, v76
	s_waitcnt lgkmcnt(2)
	v_med3_f32 v80, v90, s40, v76
	v_mov_b32_e32 v78, v5
	ds_read2_b32 v[92:93], v4 offset0:36 offset1:52
	ds_read2_b32 v[94:95], v4 offset0:101 offset1:117
	v_cvt_pk_fp8_f32 v78, v79, v80
	s_waitcnt lgkmcnt(3)
	v_med3_f32 v79, v82, s40, v76
	s_waitcnt lgkmcnt(2)
	v_med3_f32 v80, v84, s40, v76
	ds_read2_b32 v[96:97], v4 offset0:166 offset1:182
	ds_read2_b32 v[98:99], v4 offset0:231 offset1:247
	v_cvt_pk_fp8_f32 v78, v79, v80 op_sel:[0,0,1]
	s_waitcnt lgkmcnt(3)
	v_med3_f32 v80, v92, s40, v76
	s_waitcnt lgkmcnt(2)
	v_med3_f32 v81, v94, s40, v76
	v_mov_b32_e32 v79, v5
	ds_read2_b32 v[100:101], v77 offset0:40 offset1:56
	ds_read2_b32 v[102:103], v77 offset0:105 offset1:121
	v_cvt_pk_fp8_f32 v79, v80, v81
	ds_read2_b32 v[104:105], v77 offset0:170 offset1:186
	ds_read2_b32 v[106:107], v77 offset0:235 offset1:251
	ds_read2_b32 v[108:109], v118 offset0:44 offset1:60
	ds_read2_b32 v[110:111], v118 offset0:109 offset1:125
	s_waitcnt lgkmcnt(7)
	v_med3_f32 v4, v96, s40, v76
	s_waitcnt lgkmcnt(6)
	v_med3_f32 v80, v98, s40, v76
	v_cvt_pk_fp8_f32 v79, v4, v80 op_sel:[0,0,1]
	s_waitcnt lgkmcnt(5)
	v_med3_f32 v4, v100, s40, v76
	s_waitcnt lgkmcnt(4)
	v_med3_f32 v81, v102, s40, v76
	v_mov_b32_e32 v80, v5
	ds_read2_b32 v[112:113], v118 offset0:174 offset1:190
	ds_read2_b32 v[114:115], v118 offset0:239 offset1:255
	v_cvt_pk_fp8_f32 v80, v4, v81
	s_waitcnt lgkmcnt(3)
	v_med3_f32 v82, v108, s40, v76
	s_waitcnt lgkmcnt(2)
	v_med3_f32 v84, v110, s40, v76
	v_mov_b32_e32 v81, v5
	v_cvt_pk_fp8_f32 v81, v82, v84
	v_med3_f32 v4, v104, s40, v76
	v_med3_f32 v77, v106, s40, v76
	v_cvt_pk_fp8_f32 v80, v4, v77 op_sel:[0,0,1]
	s_waitcnt lgkmcnt(1)
	v_med3_f32 v4, v112, s40, v76
	s_waitcnt lgkmcnt(0)
	v_med3_f32 v77, v114, s40, v76
	v_cvt_pk_fp8_f32 v81, v4, v77 op_sel:[0,0,1]
	v_med3_f32 v4, v89, s40, v76
	v_med3_f32 v77, v91, s40, v76
	v_mov_b32_e32 v82, v5
	v_cvt_pk_fp8_f32 v82, v4, v77
	v_med3_f32 v4, v83, s40, v76
	v_med3_f32 v77, v85, s40, v76
	v_med3_f32 v84, v93, s40, v76
	v_med3_f32 v85, v95, s40, v76
	v_mov_b32_e32 v83, v5
	v_cvt_pk_fp8_f32 v83, v84, v85
	v_cvt_pk_fp8_f32 v82, v4, v77 op_sel:[0,0,1]
	v_med3_f32 v4, v97, s40, v76
	v_med3_f32 v77, v99, s40, v76
	v_cvt_pk_fp8_f32 v83, v4, v77 op_sel:[0,0,1]
	v_med3_f32 v4, v101, s40, v76
	v_med3_f32 v77, v103, s40, v76
	v_mov_b32_e32 v84, v5
	v_cvt_pk_fp8_f32 v84, v4, v77
	v_med3_f32 v88, v109, s40, v76
	v_med3_f32 v89, v111, s40, v76
	v_mov_b32_e32 v85, v5
	v_cvt_pk_fp8_f32 v85, v88, v89
	v_med3_f32 v4, v105, s40, v76
	v_med3_f32 v77, v107, s40, v76
	v_cvt_pk_fp8_f32 v84, v4, v77 op_sel:[0,0,1]
	v_med3_f32 v4, v113, s40, v76
	v_med3_f32 v77, v115, s40, v76
	v_cvt_pk_fp8_f32 v85, v4, v77 op_sel:[0,0,1]
	v_lshl_add_u64 v[88:89], v[86:87], 0, v[20:21]
	global_store_dwordx4 v[88:89], v[78:81], off nt
	v_readlane_b32 s59, v234, 26
	v_readlane_b32 s60, v234, 27
	v_lshl_add_u64 v[78:79], v[86:87], 0, v[22:23]
	global_store_dwordx4 v[78:79], v[82:85], off nt
	s_waitcnt lgkmcnt(0)
	v_readlane_b32 s61, v234, 28
	v_readlane_b32 s62, v234, 29
	v_readlane_b32 s63, v234, 30
	v_readlane_b32 s64, v234, 31
	v_readlane_b32 s65, v234, 32
	v_readlane_b32 s68, v234, 35
	v_readlane_b32 s69, v234, 36
	v_readlane_b32 s70, v234, 37
	v_readlane_b32 s71, v234, 38

.LBB0_39:
	s_andn2_b64 vcc, exec, s[10:11]
	s_cbranch_vccnz .LBB0_41
	s_and_b32 s0, s9, 0x7fc0
	s_addk_i32 s0, 0xba00
	v_readlane_b32 s56, v234, 23
	s_and_b32 s12, s5, 0x3c0
	s_lshl_b64 s[10:11], s[0:1], 12
	v_readlane_b32 s62, v234, 29
	v_readlane_b32 s63, v234, 30
	s_add_u32 s10, s62, s10
	s_addc_u32 s11, s63, s11
	s_lshl_b32 s13, s12, 2
	s_add_u32 s10, s10, s13
	s_addc_u32 s11, s11, 0
	v_lshl_add_u64 v[78:79], s[10:11], 0, v[66:67]
	v_lshlrev_b32_e32 v4, 2, v2
	v_lshl_add_u64 v[134:135], v[78:79], 0, v[4:5]
	v_add_co_u32_e32 v82, vcc, s21, v134
	global_load_dwordx4 v[78:81], v[134:135], off nt
	s_nop 0
	v_addc_co_u32_e32 v83, vcc, 0, v135, vcc
	v_add_co_u32_e32 v86, vcc, s24, v134
	global_load_dwordx4 v[82:85], v[82:83], off nt
	s_nop 0
	v_addc_co_u32_e32 v87, vcc, 0, v135, vcc
	v_add_co_u32_e32 v90, vcc, s25, v134
	global_load_dwordx4 v[86:89], v[86:87], off nt
	s_nop 0
	v_addc_co_u32_e32 v91, vcc, 0, v135, vcc
	v_add_co_u32_e32 v94, vcc, s26, v134
	global_load_dwordx4 v[90:93], v[90:91], off nt
	s_nop 0
	v_addc_co_u32_e32 v95, vcc, 0, v135, vcc
	v_add_co_u32_e32 v98, vcc, s27, v134
	global_load_dwordx4 v[94:97], v[94:95], off nt
	s_nop 0
	v_addc_co_u32_e32 v99, vcc, 0, v135, vcc
	v_add_co_u32_e32 v102, vcc, s28, v134
	global_load_dwordx4 v[98:101], v[98:99], off nt
	s_nop 0
	v_addc_co_u32_e32 v103, vcc, 0, v135, vcc
	v_add_co_u32_e32 v106, vcc, s29, v134
	global_load_dwordx4 v[102:105], v[102:103], off nt
	s_nop 0
	v_addc_co_u32_e32 v107, vcc, 0, v135, vcc
	v_add_co_u32_e32 v110, vcc, s30, v134
	global_load_dwordx4 v[106:109], v[106:107], off nt
	s_nop 0
	v_addc_co_u32_e32 v111, vcc, 0, v135, vcc
	v_add_co_u32_e32 v114, vcc, s31, v134
	global_load_dwordx4 v[110:113], v[110:111], off nt
	s_nop 0
	v_addc_co_u32_e32 v115, vcc, 0, v135, vcc
	v_add_co_u32_e32 v118, vcc, s34, v134
	global_load_dwordx4 v[114:117], v[114:115], off nt
	s_nop 0
	v_addc_co_u32_e32 v119, vcc, 0, v135, vcc
	v_add_co_u32_e32 v122, vcc, s35, v134
	v_add_u32_e32 v4, 0x410, v1
	s_nop 0
	v_addc_co_u32_e32 v123, vcc, 0, v135, vcc
	global_load_dwordx4 v[118:121], v[118:119], off nt
	s_nop 0
	global_load_dwordx4 v[122:125], v[122:123], off nt
	v_add_co_u32_e32 v126, vcc, s36, v134
	s_mulk_i32 s12, 0xb00
	s_nop 0
	v_addc_co_u32_e32 v127, vcc, 0, v135, vcc
	v_add_co_u32_e32 v130, vcc, s37, v134
	v_readlane_b32 s10, v234, 43
	s_nop 0
	v_addc_co_u32_e32 v131, vcc, 0, v135, vcc
	global_load_dwordx4 v[126:129], v[126:127], off nt
	s_nop 0
	global_load_dwordx4 v[130:133], v[130:131], off nt
	v_add_co_u32_e32 v136, vcc, s38, v134
	s_add_u32 s10, s10, s12
	s_nop 0
	v_addc_co_u32_e32 v137, vcc, 0, v135, vcc
	v_add_co_u32_e32 v138, vcc, s39, v134
	v_readlane_b32 s11, v234, 44
	s_nop 0
	v_addc_co_u32_e32 v139, vcc, 0, v135, vcc
	global_load_dwordx4 v[134:137], v[136:137], off nt
	s_nop 0
	global_load_dwordx4 v[138:141], v[138:139], off nt
	s_addc_u32 s11, s11, 0
	s_add_u32 s10, s10, s0
	s_addc_u32 s11, s11, 0
	v_readlane_b32 s57, v234, 24
	s_waitcnt vmcnt(15)
	v_pk_mul_f32 v[78:79], v[78:79], s[4:5] op_sel_hi:[1,0]
	ds_write2_b32 v1, v78, v79 offset1:1
	v_pk_mul_f32 v[78:79], v[80:81], s[4:5] op_sel_hi:[1,0]
	ds_write2_b32 v1, v78, v79 offset0:2 offset1:3
	v_readlane_b32 s58, v234, 25
	s_waitcnt vmcnt(14)
	v_pk_mul_f32 v[78:79], v[82:83], s[4:5] op_sel_hi:[1,0]
	ds_write2_b32 v4, v78, v79 offset1:1
	v_pk_mul_f32 v[78:79], v[84:85], s[4:5] op_sel_hi:[1,0]
	v_add_u32_e32 v4, 0x418, v1
	ds_write2_b32 v4, v78, v79 offset1:1
	s_waitcnt vmcnt(13)
	v_pk_mul_f32 v[78:79], v[86:87], s[4:5] op_sel_hi:[1,0]
	v_add_u32_e32 v4, 0x820, v1
	ds_write2_b32 v4, v78, v79 offset1:1
	v_pk_mul_f32 v[78:79], v[88:89], s[4:5] op_sel_hi:[1,0]
	v_add_u32_e32 v4, 0x828, v1
	ds_write2_b32 v4, v78, v79 offset1:1
	s_waitcnt vmcnt(12)
	v_pk_mul_f32 v[78:79], v[90:91], s[4:5] op_sel_hi:[1,0]
	v_add_u32_e32 v4, 0xc30, v1
	ds_write2_b32 v4, v78, v79 offset1:1
	v_pk_mul_f32 v[78:79], v[92:93], s[4:5] op_sel_hi:[1,0]
	v_add_u32_e32 v4, 0xc38, v1
	ds_write2_b32 v4, v78, v79 offset1:1
	s_waitcnt vmcnt(11)
	v_pk_mul_f32 v[78:79], v[94:95], s[4:5] op_sel_hi:[1,0]
	v_add_u32_e32 v4, 0x1040, v1
	ds_write2_b32 v4, v78, v79 offset1:1
	v_pk_mul_f32 v[78:79], v[96:97], s[4:5] op_sel_hi:[1,0]
	v_add_u32_e32 v4, 0x1048, v1
	ds_write2_b32 v4, v78, v79 offset1:1
	s_waitcnt vmcnt(10)
	v_pk_mul_f32 v[78:79], v[98:99], s[4:5] op_sel_hi:[1,0]
	v_add_u32_e32 v4, 0x1450, v1
	ds_write2_b32 v4, v78, v79 offset1:1
	v_pk_mul_f32 v[78:79], v[100:101], s[4:5] op_sel_hi:[1,0]
	v_add_u32_e32 v4, 0x1458, v1
	ds_write2_b32 v4, v78, v79 offset1:1
	s_waitcnt vmcnt(9)
	v_pk_mul_f32 v[78:79], v[102:103], s[4:5] op_sel_hi:[1,0]
	v_add_u32_e32 v4, 0x1860, v1
	ds_write2_b32 v4, v78, v79 offset1:1
	v_pk_mul_f32 v[78:79], v[104:105], s[4:5] op_sel_hi:[1,0]
	v_add_u32_e32 v4, 0x1868, v1
	ds_write2_b32 v4, v78, v79 offset1:1
	s_waitcnt vmcnt(8)
	v_pk_mul_f32 v[78:79], v[106:107], s[4:5] op_sel_hi:[1,0]
	v_add_u32_e32 v4, 0x1c70, v1
	ds_write2_b32 v4, v78, v79 offset1:1
	v_pk_mul_f32 v[78:79], v[108:109], s[4:5] op_sel_hi:[1,0]
	v_add_u32_e32 v4, 0x1c78, v1
	ds_write2_b32 v4, v78, v79 offset1:1
	s_waitcnt vmcnt(7)
	v_pk_mul_f32 v[78:79], v[110:111], s[4:5] op_sel_hi:[1,0]
	v_add_u32_e32 v4, 0x2080, v1
	ds_write2_b32 v4, v78, v79 offset1:1
	v_pk_mul_f32 v[78:79], v[112:113], s[4:5] op_sel_hi:[1,0]
	v_add_u32_e32 v4, 0x2088, v1
	ds_write2_b32 v4, v78, v79 offset1:1
	s_waitcnt vmcnt(6)
	v_pk_mul_f32 v[78:79], v[114:115], s[4:5] op_sel_hi:[1,0]
	v_add_u32_e32 v4, 0x2490, v1
	ds_write2_b32 v4, v78, v79 offset1:1
	v_pk_mul_f32 v[78:79], v[116:117], s[4:5] op_sel_hi:[1,0]
	v_add_u32_e32 v4, 0x2498, v1
	ds_write2_b32 v4, v78, v79 offset1:1
	s_waitcnt vmcnt(5)
	v_pk_mul_f32 v[78:79], v[118:119], s[4:5] op_sel_hi:[1,0]
	v_add_u32_e32 v4, 0x28a0, v1
	ds_write2_b32 v4, v78, v79 offset1:1
	v_pk_mul_f32 v[78:79], v[120:121], s[4:5] op_sel_hi:[1,0]
	v_add_u32_e32 v4, 0x28a8, v1
	ds_write2_b32 v4, v78, v79 offset1:1
	s_waitcnt vmcnt(4)
	v_pk_mul_f32 v[78:79], v[122:123], s[4:5] op_sel_hi:[1,0]
	v_add_u32_e32 v4, 0x2cb0, v1
	ds_write2_b32 v4, v78, v79 offset1:1
	v_pk_mul_f32 v[78:79], v[124:125], s[4:5] op_sel_hi:[1,0]
	v_add_u32_e32 v4, 0x2cb8, v1
	ds_write2_b32 v4, v78, v79 offset1:1
	s_waitcnt vmcnt(3)
	v_pk_mul_f32 v[78:79], v[126:127], s[4:5] op_sel_hi:[1,0]
	v_add_u32_e32 v4, 0x30c0, v1
	ds_write2_b32 v4, v78, v79 offset1:1
	v_pk_mul_f32 v[78:79], v[128:129], s[4:5] op_sel_hi:[1,0]
	v_add_u32_e32 v4, 0x30c8, v1
	ds_write2_b32 v4, v78, v79 offset1:1
	s_waitcnt vmcnt(2)
	v_pk_mul_f32 v[78:79], v[130:131], s[4:5] op_sel_hi:[1,0]
	v_add_u32_e32 v4, 0x34d0, v1
	ds_write2_b32 v4, v78, v79 offset1:1
	v_pk_mul_f32 v[78:79], v[132:133], s[4:5] op_sel_hi:[1,0]
	v_add_u32_e32 v4, 0x34d8, v1
	ds_write2_b32 v4, v78, v79 offset1:1
	s_waitcnt vmcnt(1)
	v_pk_mul_f32 v[78:79], v[134:135], s[4:5] op_sel_hi:[1,0]
	v_add_u32_e32 v4, 0x38e0, v1
	ds_write2_b32 v4, v78, v79 offset1:1
	v_pk_mul_f32 v[78:79], v[136:137], s[4:5] op_sel_hi:[1,0]
	v_add_u32_e32 v4, 0x38e8, v1
	ds_write2_b32 v4, v78, v79 offset1:1
	s_waitcnt vmcnt(0)
	v_pk_mul_f32 v[78:79], v[138:139], s[4:5] op_sel_hi:[1,0]
	v_add_u32_e32 v4, 0x3cf0, v1
	ds_write2_b32 v4, v78, v79 offset1:1
	v_pk_mul_f32 v[78:79], v[140:141], s[4:5] op_sel_hi:[1,0]
	v_add_u32_e32 v4, 0x3cf8, v1
	ds_write2_b32 v4, v78, v79 offset1:1
	s_waitcnt lgkmcnt(0)
	ds_read2_b32 v[82:83], v3 offset1:16
	ds_read2_b32 v[84:85], v3 offset0:65 offset1:81
	v_mov_b32_e32 v78, v5
	ds_read2_b32 v[88:89], v3 offset0:130 offset1:146
	ds_read2_b32 v[90:91], v3 offset0:195 offset1:211
	v_add_u32_e32 v118, 0xc00, v3
	s_waitcnt lgkmcnt(3)
	v_med3_f32 v4, v82, s40, v76
	s_waitcnt lgkmcnt(2)
	v_med3_f32 v77, v84, s40, v76
	v_cvt_pk_fp8_f32 v78, v4, v77
	v_add_u32_e32 v4, 0x400, v3
	ds_read2_b32 v[92:93], v4 offset0:4 offset1:20
	ds_read2_b32 v[94:95], v4 offset0:69 offset1:85
	s_waitcnt lgkmcnt(3)
	v_med3_f32 v77, v88, s40, v76
	s_waitcnt lgkmcnt(2)
	v_med3_f32 v79, v90, s40, v76
	v_cvt_pk_fp8_f32 v78, v77, v79 op_sel:[0,0,1]
	s_waitcnt lgkmcnt(1)
	v_med3_f32 v77, v92, s40, v76
	s_waitcnt lgkmcnt(0)
	v_med3_f32 v80, v94, s40, v76
	v_mov_b32_e32 v79, v5
	v_cvt_pk_fp8_f32 v79, v77, v80
	ds_read2_b32 v[96:97], v4 offset0:134 offset1:150
	ds_read2_b32 v[98:99], v4 offset0:199 offset1:215
	v_add_u32_e32 v77, 0x800, v3
	ds_read2_b32 v[100:101], v77 offset0:8 offset1:24
	ds_read2_b32 v[102:103], v77 offset0:73 offset1:89
	ds_read2_b32 v[104:105], v77 offset0:138 offset1:154
	ds_read2_b32 v[106:107], v77 offset0:203 offset1:219
	ds_read2_b32 v[108:109], v118 offset0:12 offset1:28
	ds_read2_b32 v[110:111], v118 offset0:77 offset1:93
	s_waitcnt lgkmcnt(7)
	v_med3_f32 v80, v96, s40, v76
	s_waitcnt lgkmcnt(6)
	v_med3_f32 v81, v98, s40, v76
	v_cvt_pk_fp8_f32 v79, v80, v81 op_sel:[0,0,1]
	s_waitcnt lgkmcnt(5)
	v_med3_f32 v81, v100, s40, v76
	s_waitcnt lgkmcnt(4)
	v_med3_f32 v82, v102, s40, v76
	v_mov_b32_e32 v80, v5
	ds_read2_b32 v[112:113], v118 offset0:142 offset1:158
	ds_read2_b32 v[114:115], v118 offset0:207 offset1:223
	v_cvt_pk_fp8_f32 v80, v81, v82
	s_waitcnt lgkmcnt(3)
	v_med3_f32 v88, v108, s40, v76
	s_waitcnt lgkmcnt(2)
	v_med3_f32 v90, v110, s40, v76
	v_mov_b32_e32 v81, v5
	v_cvt_pk_fp8_f32 v81, v88, v90
	v_med3_f32 v82, v104, s40, v76
	v_med3_f32 v84, v106, s40, v76
	v_cvt_pk_fp8_f32 v80, v82, v84 op_sel:[0,0,1]
	s_waitcnt lgkmcnt(1)
	v_med3_f32 v82, v112, s40, v76
	s_waitcnt lgkmcnt(0)
	v_med3_f32 v84, v114, s40, v76
	v_cvt_pk_fp8_f32 v81, v82, v84 op_sel:[0,0,1]
	v_med3_f32 v83, v83, s40, v76
	v_med3_f32 v84, v85, s40, v76
	v_mov_b32_e32 v82, v5
	v_cvt_pk_fp8_f32 v82, v83, v84
	v_med3_f32 v84, v89, s40, v76
	v_med3_f32 v88, v93, s40, v76
	v_med3_f32 v89, v95, s40, v76
	v_mov_b32_e32 v83, v5
	v_cvt_pk_fp8_f32 v83, v88, v89
	v_med3_f32 v85, v91, s40, v76
	v_cvt_pk_fp8_f32 v82, v84, v85 op_sel:[0,0,1]
	v_med3_f32 v84, v97, s40, v76
	v_med3_f32 v85, v99, s40, v76
	v_cvt_pk_fp8_f32 v83, v84, v85 op_sel:[0,0,1]
	v_med3_f32 v85, v101, s40, v76
	v_med3_f32 v88, v103, s40, v76
	v_mov_b32_e32 v84, v5
	v_cvt_pk_fp8_f32 v84, v85, v88
	v_med3_f32 v90, v109, s40, v76
	v_med3_f32 v91, v111, s40, v76
	v_mov_b32_e32 v85, v5
	v_cvt_pk_fp8_f32 v85, v90, v91
	v_med3_f32 v88, v105, s40, v76
	v_med3_f32 v89, v107, s40, v76
	v_cvt_pk_fp8_f32 v84, v88, v89 op_sel:[0,0,1]
	v_med3_f32 v88, v113, s40, v76
	v_med3_f32 v89, v115, s40, v76
	v_cvt_pk_fp8_f32 v85, v88, v89 op_sel:[0,0,1]
	v_lshl_add_u64 v[86:87], s[10:11], 0, v[6:7]
	ds_read2_b32 v[88:89], v3 offset0:32 offset1:48
	ds_read2_b32 v[90:91], v3 offset0:97 offset1:113
	v_lshl_add_u64 v[116:117], v[86:87], 0, v[24:25]
	global_store_dwordx4 v[116:117], v[78:81], off nt
	v_readlane_b32 s59, v234, 26
	v_readlane_b32 s60, v234, 27
	v_lshl_add_u64 v[78:79], v[86:87], 0, v[26:27]
	global_store_dwordx4 v[78:79], v[82:85], off nt
	ds_read2_b32 v[82:83], v3 offset0:162 offset1:178
	ds_read2_b32 v[84:85], v3 offset0:227 offset1:243
	s_waitcnt lgkmcnt(3)
	v_med3_f32 v79, v88, s40, v76
	s_waitcnt lgkmcnt(2)
	v_med3_f32 v80, v90, s40, v76
	v_mov_b32_e32 v78, v5
	ds_read2_b32 v[92:93], v4 offset0:36 offset1:52
	ds_read2_b32 v[94:95], v4 offset0:101 offset1:117
	v_cvt_pk_fp8_f32 v78, v79, v80
	s_waitcnt lgkmcnt(3)
	v_med3_f32 v79, v82, s40, v76
	s_waitcnt lgkmcnt(2)
	v_med3_f32 v80, v84, s40, v76
	ds_read2_b32 v[96:97], v4 offset0:166 offset1:182
	ds_read2_b32 v[98:99], v4 offset0:231 offset1:247
	v_cvt_pk_fp8_f32 v78, v79, v80 op_sel:[0,0,1]
	s_waitcnt lgkmcnt(3)
	v_med3_f32 v80, v92, s40, v76
	s_waitcnt lgkmcnt(2)
	v_med3_f32 v81, v94, s40, v76
	v_mov_b32_e32 v79, v5
	ds_read2_b32 v[100:101], v77 offset0:40 offset1:56
	ds_read2_b32 v[102:103], v77 offset0:105 offset1:121
	v_cvt_pk_fp8_f32 v79, v80, v81
	ds_read2_b32 v[104:105], v77 offset0:170 offset1:186
	ds_read2_b32 v[106:107], v77 offset0:235 offset1:251
	ds_read2_b32 v[108:109], v118 offset0:44 offset1:60
	ds_read2_b32 v[110:111], v118 offset0:109 offset1:125
	s_waitcnt lgkmcnt(7)
	v_med3_f32 v4, v96, s40, v76
	s_waitcnt lgkmcnt(6)
	v_med3_f32 v80, v98, s40, v76
	v_cvt_pk_fp8_f32 v79, v4, v80 op_sel:[0,0,1]
	s_waitcnt lgkmcnt(5)
	v_med3_f32 v4, v100, s40, v76
	s_waitcnt lgkmcnt(4)
	v_med3_f32 v81, v102, s40, v76
	v_mov_b32_e32 v80, v5
	ds_read2_b32 v[112:113], v118 offset0:174 offset1:190
	ds_read2_b32 v[114:115], v118 offset0:239 offset1:255
	v_cvt_pk_fp8_f32 v80, v4, v81
	s_waitcnt lgkmcnt(3)
	v_med3_f32 v82, v108, s40, v76
	s_waitcnt lgkmcnt(2)
	v_med3_f32 v84, v110, s40, v76
	v_mov_b32_e32 v81, v5
	v_cvt_pk_fp8_f32 v81, v82, v84
	v_med3_f32 v4, v104, s40, v76
	v_med3_f32 v77, v106, s40, v76
	v_cvt_pk_fp8_f32 v80, v4, v77 op_sel:[0,0,1]
	s_waitcnt lgkmcnt(1)
	v_med3_f32 v4, v112, s40, v76
	s_waitcnt lgkmcnt(0)
	v_med3_f32 v77, v114, s40, v76
	v_cvt_pk_fp8_f32 v81, v4, v77 op_sel:[0,0,1]
	v_med3_f32 v4, v89, s40, v76
	v_med3_f32 v77, v91, s40, v76
	v_mov_b32_e32 v82, v5
	v_cvt_pk_fp8_f32 v82, v4, v77
	v_med3_f32 v4, v83, s40, v76
	v_med3_f32 v77, v85, s40, v76
	v_med3_f32 v84, v93, s40, v76
	v_med3_f32 v85, v95, s40, v76
	v_mov_b32_e32 v83, v5
	v_cvt_pk_fp8_f32 v83, v84, v85
	v_cvt_pk_fp8_f32 v82, v4, v77 op_sel:[0,0,1]
	v_med3_f32 v4, v97, s40, v76
	v_med3_f32 v77, v99, s40, v76
	v_cvt_pk_fp8_f32 v83, v4, v77 op_sel:[0,0,1]
	v_med3_f32 v4, v101, s40, v76
	v_med3_f32 v77, v103, s40, v76
	v_mov_b32_e32 v84, v5
	v_cvt_pk_fp8_f32 v84, v4, v77
	v_med3_f32 v88, v109, s40, v76
	v_med3_f32 v89, v111, s40, v76
	v_mov_b32_e32 v85, v5
	v_cvt_pk_fp8_f32 v85, v88, v89
	v_med3_f32 v4, v105, s40, v76
	v_med3_f32 v77, v107, s40, v76
	v_cvt_pk_fp8_f32 v84, v4, v77 op_sel:[0,0,1]
	v_med3_f32 v4, v113, s40, v76
	v_med3_f32 v77, v115, s40, v76
	v_cvt_pk_fp8_f32 v85, v4, v77 op_sel:[0,0,1]
	v_lshl_add_u64 v[88:89], v[86:87], 0, v[28:29]
	global_store_dwordx4 v[88:89], v[78:81], off nt
	v_readlane_b32 s61, v234, 28
	v_readlane_b32 s64, v234, 31
	v_lshl_add_u64 v[78:79], v[86:87], 0, v[30:31]
	global_store_dwordx4 v[78:79], v[82:85], off nt
	s_waitcnt lgkmcnt(0)
	v_readlane_b32 s65, v234, 32
	v_readlane_b32 s66, v234, 33
	v_readlane_b32 s67, v234, 34
	v_readlane_b32 s68, v234, 35
	v_readlane_b32 s69, v234, 36
	v_readlane_b32 s70, v234, 37
	v_readlane_b32 s71, v234, 38

.LBB0_47:
	s_lshl_b32 s10, s12, 6
	v_readlane_b32 s56, v234, 23
	s_and_b32 s10, s10, 0xffc0
	s_mul_i32 s12, s12, 0x160000
	v_readlane_b32 s60, v234, 27
	v_readlane_b32 s61, v234, 28
	s_add_u32 s11, s60, s12
	s_addc_u32 s14, s61, 0
	s_and_b32 s12, 0xffff, s13
	s_lshl_b32 s12, s12, 2
	s_add_u32 s12, s11, s12
	s_addc_u32 s13, s14, 0
	v_lshl_add_u64 v[78:79], s[12:13], 0, v[70:71]
	v_lshlrev_b32_e32 v4, 2, v2
	v_lshl_add_u64 v[134:135], v[78:79], 0, v[4:5]
	s_mov_b32 s11, 0x16000
	v_add_co_u32_e32 v82, vcc, s11, v134
	s_mov_b32 s11, 0x42000
	s_nop 0
	v_addc_co_u32_e32 v83, vcc, 0, v135, vcc
	global_load_dwordx4 v[78:81], v[134:135], off nt
	s_nop 0
	global_load_dwordx4 v[82:85], v[82:83], off nt
	v_add_co_u32_e32 v86, vcc, s35, v134
	s_lshl_b64 s[12:13], s[0:1], 10
	s_nop 0
	v_addc_co_u32_e32 v87, vcc, 0, v135, vcc
	v_add_co_u32_e32 v90, vcc, s11, v134
	s_mov_b32 s11, 0x6e000
	s_nop 0
	v_addc_co_u32_e32 v91, vcc, 0, v135, vcc
	global_load_dwordx4 v[86:89], v[86:87], off nt
	s_nop 0
	global_load_dwordx4 v[90:93], v[90:91], off nt
	v_add_co_u32_e32 v94, vcc, s45, v134
	v_readlane_b32 s0, v234, 45
	s_nop 0
	v_addc_co_u32_e32 v95, vcc, 0, v135, vcc
	v_add_co_u32_e32 v98, vcc, s11, v134
	s_add_u32 s0, s0, s12
	s_nop 0
	v_addc_co_u32_e32 v99, vcc, 0, v135, vcc
	s_mov_b32 s12, 0x84000
	global_load_dwordx4 v[94:97], v[94:95], off nt
	s_nop 0
	global_load_dwordx4 v[98:101], v[98:99], off nt
	v_add_co_u32_e32 v102, vcc, s12, v134
	s_mov_b32 s12, 0x9a000
	s_nop 0
	v_addc_co_u32_e32 v103, vcc, 0, v135, vcc
	v_add_co_u32_e32 v106, vcc, s12, v134
	s_mov_b32 s12, 0xb0000
	s_nop 0
	v_addc_co_u32_e32 v107, vcc, 0, v135, vcc
	global_load_dwordx4 v[102:105], v[102:103], off nt
	s_nop 0
	global_load_dwordx4 v[106:109], v[106:107], off nt
	v_add_co_u32_e32 v110, vcc, s12, v134
	s_mov_b32 s12, 0xc6000
	s_nop 0
	v_addc_co_u32_e32 v111, vcc, 0, v135, vcc
	v_add_co_u32_e32 v114, vcc, s12, v134
	s_mov_b32 s12, 0xdc000
	s_nop 0
	v_addc_co_u32_e32 v115, vcc, 0, v135, vcc
	global_load_dwordx4 v[110:113], v[110:111], off nt
	s_nop 0
	global_load_dwordx4 v[114:117], v[114:115], off nt
	v_add_co_u32_e32 v118, vcc, s12, v134
	s_mov_b32 s12, 0xf2000
	s_nop 0
	v_addc_co_u32_e32 v119, vcc, 0, v135, vcc
	v_add_co_u32_e32 v122, vcc, s12, v134
	s_mov_b32 s12, 0x11e000
	s_nop 0
	v_addc_co_u32_e32 v123, vcc, 0, v135, vcc
	global_load_dwordx4 v[118:121], v[118:119], off nt
	s_nop 0
	global_load_dwordx4 v[122:125], v[122:123], off nt
	v_add_co_u32_e32 v126, vcc, s48, v134
	v_add_u32_e32 v4, 0x410, v1
	s_nop 0
	v_addc_co_u32_e32 v127, vcc, 0, v135, vcc
	v_add_co_u32_e32 v130, vcc, s12, v134
	s_mov_b32 s12, 0x14a000
	s_nop 0
	v_addc_co_u32_e32 v131, vcc, 0, v135, vcc
	global_load_dwordx4 v[126:129], v[126:127], off nt
	s_nop 0
	global_load_dwordx4 v[130:133], v[130:131], off nt
	v_add_co_u32_e32 v136, vcc, s43, v134
	v_readlane_b32 s11, v234, 46
	s_nop 0
	v_addc_co_u32_e32 v137, vcc, 0, v135, vcc
	v_add_co_u32_e32 v138, vcc, s12, v134
	s_addc_u32 s11, s11, s13
	s_nop 0
	v_addc_co_u32_e32 v139, vcc, 0, v135, vcc
	global_load_dwordx4 v[134:137], v[136:137], off nt
	s_nop 0
	global_load_dwordx4 v[138:141], v[138:139], off nt
	s_waitcnt vmcnt(15)
	v_pk_mul_f32 v[78:79], v[78:79], s[6:7] op_sel_hi:[1,0]
	ds_write2_b32 v1, v78, v79 offset1:1
	v_pk_mul_f32 v[78:79], v[80:81], s[6:7] op_sel_hi:[1,0]
	ds_write2_b32 v1, v78, v79 offset0:2 offset1:3
	s_waitcnt vmcnt(14)
	v_pk_mul_f32 v[78:79], v[82:83], s[6:7] op_sel_hi:[1,0]
	ds_write2_b32 v4, v78, v79 offset1:1
	v_pk_mul_f32 v[78:79], v[84:85], s[6:7] op_sel_hi:[1,0]
	v_add_u32_e32 v4, 0x418, v1
	ds_write2_b32 v4, v78, v79 offset1:1
	v_add_u32_e32 v4, 0x820, v1
	s_add_u32 s10, s0, s10
	s_waitcnt vmcnt(13)
	v_pk_mul_f32 v[78:79], v[86:87], s[6:7] op_sel_hi:[1,0]
	ds_write2_b32 v4, v78, v79 offset1:1
	v_pk_mul_f32 v[78:79], v[88:89], s[6:7] op_sel_hi:[1,0]
	v_add_u32_e32 v4, 0x828, v1
	ds_write2_b32 v4, v78, v79 offset1:1
	s_waitcnt vmcnt(12)
	v_pk_mul_f32 v[78:79], v[90:91], s[6:7] op_sel_hi:[1,0]
	v_add_u32_e32 v4, 0xc30, v1
	ds_write2_b32 v4, v78, v79 offset1:1
	v_pk_mul_f32 v[78:79], v[92:93], s[6:7] op_sel_hi:[1,0]
	v_add_u32_e32 v4, 0xc38, v1
	ds_write2_b32 v4, v78, v79 offset1:1
	v_add_u32_e32 v4, 0x1040, v1
	s_waitcnt vmcnt(11)
	v_pk_mul_f32 v[78:79], v[94:95], s[6:7] op_sel_hi:[1,0]
	ds_write2_b32 v4, v78, v79 offset1:1
	v_pk_mul_f32 v[78:79], v[96:97], s[6:7] op_sel_hi:[1,0]
	v_add_u32_e32 v4, 0x1048, v1
	ds_write2_b32 v4, v78, v79 offset1:1
	s_waitcnt vmcnt(10)
	v_pk_mul_f32 v[78:79], v[98:99], s[6:7] op_sel_hi:[1,0]
	v_add_u32_e32 v4, 0x1450, v1
	ds_write2_b32 v4, v78, v79 offset1:1
	v_pk_mul_f32 v[78:79], v[100:101], s[6:7] op_sel_hi:[1,0]
	v_add_u32_e32 v4, 0x1458, v1
	ds_write2_b32 v4, v78, v79 offset1:1
	s_waitcnt vmcnt(9)
	v_pk_mul_f32 v[78:79], v[102:103], s[6:7] op_sel_hi:[1,0]
	v_add_u32_e32 v4, 0x1860, v1
	ds_write2_b32 v4, v78, v79 offset1:1
	v_pk_mul_f32 v[78:79], v[104:105], s[6:7] op_sel_hi:[1,0]
	v_add_u32_e32 v4, 0x1868, v1
	ds_write2_b32 v4, v78, v79 offset1:1
	s_waitcnt vmcnt(8)
	v_pk_mul_f32 v[78:79], v[106:107], s[6:7] op_sel_hi:[1,0]
	v_add_u32_e32 v4, 0x1c70, v1
	ds_write2_b32 v4, v78, v79 offset1:1
	v_pk_mul_f32 v[78:79], v[108:109], s[6:7] op_sel_hi:[1,0]
	v_add_u32_e32 v4, 0x1c78, v1
	ds_write2_b32 v4, v78, v79 offset1:1
	s_waitcnt vmcnt(7)
	v_pk_mul_f32 v[78:79], v[110:111], s[6:7] op_sel_hi:[1,0]
	v_add_u32_e32 v4, 0x2080, v1
	ds_write2_b32 v4, v78, v79 offset1:1
	v_pk_mul_f32 v[78:79], v[112:113], s[6:7] op_sel_hi:[1,0]
	v_add_u32_e32 v4, 0x2088, v1
	ds_write2_b32 v4, v78, v79 offset1:1
	s_waitcnt vmcnt(6)
	v_pk_mul_f32 v[78:79], v[114:115], s[6:7] op_sel_hi:[1,0]
	v_add_u32_e32 v4, 0x2490, v1
	ds_write2_b32 v4, v78, v79 offset1:1
	v_pk_mul_f32 v[78:79], v[116:117], s[6:7] op_sel_hi:[1,0]
	v_add_u32_e32 v4, 0x2498, v1
	ds_write2_b32 v4, v78, v79 offset1:1
	s_waitcnt vmcnt(5)
	v_pk_mul_f32 v[78:79], v[118:119], s[6:7] op_sel_hi:[1,0]
	v_add_u32_e32 v4, 0x28a0, v1
	ds_write2_b32 v4, v78, v79 offset1:1
	v_pk_mul_f32 v[78:79], v[120:121], s[6:7] op_sel_hi:[1,0]
	v_add_u32_e32 v4, 0x28a8, v1
	ds_write2_b32 v4, v78, v79 offset1:1
	s_waitcnt vmcnt(4)
	v_pk_mul_f32 v[78:79], v[122:123], s[6:7] op_sel_hi:[1,0]
	v_add_u32_e32 v4, 0x2cb0, v1
	ds_write2_b32 v4, v78, v79 offset1:1
	v_pk_mul_f32 v[78:79], v[124:125], s[6:7] op_sel_hi:[1,0]
	v_add_u32_e32 v4, 0x2cb8, v1
	ds_write2_b32 v4, v78, v79 offset1:1
	s_waitcnt vmcnt(3)
	v_pk_mul_f32 v[78:79], v[126:127], s[6:7] op_sel_hi:[1,0]
	v_add_u32_e32 v4, 0x30c0, v1
	ds_write2_b32 v4, v78, v79 offset1:1
	v_pk_mul_f32 v[78:79], v[128:129], s[6:7] op_sel_hi:[1,0]
	v_add_u32_e32 v4, 0x30c8, v1
	ds_write2_b32 v4, v78, v79 offset1:1
	s_waitcnt vmcnt(2)
	v_pk_mul_f32 v[78:79], v[130:131], s[6:7] op_sel_hi:[1,0]
	v_add_u32_e32 v4, 0x34d0, v1
	ds_write2_b32 v4, v78, v79 offset1:1
	v_pk_mul_f32 v[78:79], v[132:133], s[6:7] op_sel_hi:[1,0]
	v_add_u32_e32 v4, 0x34d8, v1
	ds_write2_b32 v4, v78, v79 offset1:1
	s_waitcnt vmcnt(1)
	v_pk_mul_f32 v[78:79], v[134:135], s[6:7] op_sel_hi:[1,0]
	v_add_u32_e32 v4, 0x38e0, v1
	ds_write2_b32 v4, v78, v79 offset1:1
	v_pk_mul_f32 v[78:79], v[136:137], s[6:7] op_sel_hi:[1,0]
	v_add_u32_e32 v4, 0x38e8, v1
	ds_write2_b32 v4, v78, v79 offset1:1
	s_waitcnt vmcnt(0)
	v_pk_mul_f32 v[78:79], v[138:139], s[6:7] op_sel_hi:[1,0]
	v_add_u32_e32 v4, 0x3cf0, v1
	ds_write2_b32 v4, v78, v79 offset1:1
	v_pk_mul_f32 v[78:79], v[140:141], s[6:7] op_sel_hi:[1,0]
	v_add_u32_e32 v4, 0x3cf8, v1
	ds_write2_b32 v4, v78, v79 offset1:1
	s_waitcnt lgkmcnt(0)
	ds_read2_b32 v[82:83], v3 offset1:16
	ds_read2_b32 v[84:85], v3 offset0:65 offset1:81
	v_mov_b32_e32 v78, v5
	ds_read2_b32 v[88:89], v3 offset0:130 offset1:146
	ds_read2_b32 v[90:91], v3 offset0:195 offset1:211
	v_add_u32_e32 v118, 0xc00, v3
	s_waitcnt lgkmcnt(3)
	v_med3_f32 v4, v82, s40, v76
	s_waitcnt lgkmcnt(2)
	v_med3_f32 v77, v84, s40, v76
	v_cvt_pk_fp8_f32 v78, v4, v77
	v_add_u32_e32 v4, 0x400, v3
	ds_read2_b32 v[92:93], v4 offset0:4 offset1:20
	ds_read2_b32 v[94:95], v4 offset0:69 offset1:85
	s_waitcnt lgkmcnt(3)
	v_med3_f32 v77, v88, s40, v76
	s_waitcnt lgkmcnt(2)
	v_med3_f32 v79, v90, s40, v76
	v_cvt_pk_fp8_f32 v78, v77, v79 op_sel:[0,0,1]
	s_waitcnt lgkmcnt(1)
	v_med3_f32 v77, v92, s40, v76
	s_waitcnt lgkmcnt(0)
	v_med3_f32 v80, v94, s40, v76
	v_mov_b32_e32 v79, v5
	v_cvt_pk_fp8_f32 v79, v77, v80
	ds_read2_b32 v[96:97], v4 offset0:134 offset1:150
	ds_read2_b32 v[98:99], v4 offset0:199 offset1:215
	v_add_u32_e32 v77, 0x800, v3
	ds_read2_b32 v[100:101], v77 offset0:8 offset1:24
	ds_read2_b32 v[102:103], v77 offset0:73 offset1:89
	ds_read2_b32 v[104:105], v77 offset0:138 offset1:154
	ds_read2_b32 v[106:107], v77 offset0:203 offset1:219
	ds_read2_b32 v[108:109], v118 offset0:12 offset1:28
	ds_read2_b32 v[110:111], v118 offset0:77 offset1:93
	s_waitcnt lgkmcnt(7)
	v_med3_f32 v80, v96, s40, v76
	s_waitcnt lgkmcnt(6)
	v_med3_f32 v81, v98, s40, v76
	v_cvt_pk_fp8_f32 v79, v80, v81 op_sel:[0,0,1]
	s_waitcnt lgkmcnt(5)
	v_med3_f32 v81, v100, s40, v76
	s_waitcnt lgkmcnt(4)
	v_med3_f32 v82, v102, s40, v76
	v_mov_b32_e32 v80, v5
	ds_read2_b32 v[112:113], v118 offset0:142 offset1:158
	ds_read2_b32 v[114:115], v118 offset0:207 offset1:223
	v_cvt_pk_fp8_f32 v80, v81, v82
	s_waitcnt lgkmcnt(3)
	v_med3_f32 v88, v108, s40, v76
	s_waitcnt lgkmcnt(2)
	v_med3_f32 v90, v110, s40, v76
	v_mov_b32_e32 v81, v5
	v_cvt_pk_fp8_f32 v81, v88, v90
	v_med3_f32 v82, v104, s40, v76
	v_med3_f32 v84, v106, s40, v76
	v_cvt_pk_fp8_f32 v80, v82, v84 op_sel:[0,0,1]
	s_waitcnt lgkmcnt(1)
	v_med3_f32 v82, v112, s40, v76
	s_waitcnt lgkmcnt(0)
	v_med3_f32 v84, v114, s40, v76
	v_cvt_pk_fp8_f32 v81, v82, v84 op_sel:[0,0,1]
	v_med3_f32 v83, v83, s40, v76
	v_med3_f32 v84, v85, s40, v76
	v_mov_b32_e32 v82, v5
	v_cvt_pk_fp8_f32 v82, v83, v84
	v_med3_f32 v84, v89, s40, v76
	v_med3_f32 v88, v93, s40, v76
	v_med3_f32 v89, v95, s40, v76
	v_mov_b32_e32 v83, v5
	v_cvt_pk_fp8_f32 v83, v88, v89
	v_med3_f32 v85, v91, s40, v76
	v_cvt_pk_fp8_f32 v82, v84, v85 op_sel:[0,0,1]
	v_med3_f32 v84, v97, s40, v76
	v_med3_f32 v85, v99, s40, v76
	v_cvt_pk_fp8_f32 v83, v84, v85 op_sel:[0,0,1]
	v_med3_f32 v85, v101, s40, v76
	v_med3_f32 v88, v103, s40, v76
	v_mov_b32_e32 v84, v5
	v_cvt_pk_fp8_f32 v84, v85, v88
	v_med3_f32 v90, v109, s40, v76
	v_med3_f32 v91, v111, s40, v76
	v_mov_b32_e32 v85, v5
	v_cvt_pk_fp8_f32 v85, v90, v91
	v_med3_f32 v88, v105, s40, v76
	v_med3_f32 v89, v107, s40, v76
	v_cvt_pk_fp8_f32 v84, v88, v89 op_sel:[0,0,1]
	v_med3_f32 v88, v113, s40, v76
	v_med3_f32 v89, v115, s40, v76
	s_addc_u32 s11, s11, 0
	v_cvt_pk_fp8_f32 v85, v88, v89 op_sel:[0,0,1]
	v_lshl_add_u64 v[86:87], s[10:11], 0, v[6:7]
	ds_read2_b32 v[88:89], v3 offset0:32 offset1:48
	ds_read2_b32 v[90:91], v3 offset0:97 offset1:113
	v_lshl_add_u64 v[116:117], v[86:87], 0, v[16:17]
	global_store_dwordx4 v[116:117], v[78:81], off nt
	v_readlane_b32 s57, v234, 24
	v_readlane_b32 s58, v234, 25
	v_lshl_add_u64 v[78:79], v[86:87], 0, v[18:19]
	global_store_dwordx4 v[78:79], v[82:85], off nt
	ds_read2_b32 v[82:83], v3 offset0:162 offset1:178
	ds_read2_b32 v[84:85], v3 offset0:227 offset1:243
	s_waitcnt lgkmcnt(3)
	v_med3_f32 v79, v88, s40, v76
	s_waitcnt lgkmcnt(2)
	v_med3_f32 v80, v90, s40, v76
	v_mov_b32_e32 v78, v5
	ds_read2_b32 v[92:93], v4 offset0:36 offset1:52
	ds_read2_b32 v[94:95], v4 offset0:101 offset1:117
	v_cvt_pk_fp8_f32 v78, v79, v80
	s_waitcnt lgkmcnt(3)
	v_med3_f32 v79, v82, s40, v76
	s_waitcnt lgkmcnt(2)
	v_med3_f32 v80, v84, s40, v76
	ds_read2_b32 v[96:97], v4 offset0:166 offset1:182
	ds_read2_b32 v[98:99], v4 offset0:231 offset1:247
	v_cvt_pk_fp8_f32 v78, v79, v80 op_sel:[0,0,1]
	s_waitcnt lgkmcnt(3)
	v_med3_f32 v80, v92, s40, v76
	s_waitcnt lgkmcnt(2)
	v_med3_f32 v81, v94, s40, v76
	v_mov_b32_e32 v79, v5
	ds_read2_b32 v[100:101], v77 offset0:40 offset1:56
	ds_read2_b32 v[102:103], v77 offset0:105 offset1:121
	v_cvt_pk_fp8_f32 v79, v80, v81
	ds_read2_b32 v[104:105], v77 offset0:170 offset1:186
	ds_read2_b32 v[106:107], v77 offset0:235 offset1:251
	ds_read2_b32 v[108:109], v118 offset0:44 offset1:60
	ds_read2_b32 v[110:111], v118 offset0:109 offset1:125
	s_waitcnt lgkmcnt(7)
	v_med3_f32 v4, v96, s40, v76
	s_waitcnt lgkmcnt(6)
	v_med3_f32 v80, v98, s40, v76
	v_cvt_pk_fp8_f32 v79, v4, v80 op_sel:[0,0,1]
	s_waitcnt lgkmcnt(5)
	v_med3_f32 v4, v100, s40, v76
	s_waitcnt lgkmcnt(4)
	v_med3_f32 v81, v102, s40, v76
	v_mov_b32_e32 v80, v5
	ds_read2_b32 v[112:113], v118 offset0:174 offset1:190
	ds_read2_b32 v[114:115], v118 offset0:239 offset1:255
	v_cvt_pk_fp8_f32 v80, v4, v81
	s_waitcnt lgkmcnt(3)
	v_med3_f32 v82, v108, s40, v76
	s_waitcnt lgkmcnt(2)
	v_med3_f32 v84, v110, s40, v76
	v_mov_b32_e32 v81, v5
	v_cvt_pk_fp8_f32 v81, v82, v84
	v_med3_f32 v4, v104, s40, v76
	v_med3_f32 v77, v106, s40, v76
	v_cvt_pk_fp8_f32 v80, v4, v77 op_sel:[0,0,1]
	s_waitcnt lgkmcnt(1)
	v_med3_f32 v4, v112, s40, v76
	s_waitcnt lgkmcnt(0)
	v_med3_f32 v77, v114, s40, v76
	v_cvt_pk_fp8_f32 v81, v4, v77 op_sel:[0,0,1]
	v_med3_f32 v4, v89, s40, v76
	v_med3_f32 v77, v91, s40, v76
	v_mov_b32_e32 v82, v5
	v_cvt_pk_fp8_f32 v82, v4, v77
	v_med3_f32 v4, v83, s40, v76
	v_med3_f32 v77, v85, s40, v76
	v_med3_f32 v84, v93, s40, v76
	v_med3_f32 v85, v95, s40, v76
	v_mov_b32_e32 v83, v5
	v_cvt_pk_fp8_f32 v83, v84, v85
	v_cvt_pk_fp8_f32 v82, v4, v77 op_sel:[0,0,1]
	v_med3_f32 v4, v97, s40, v76
	v_med3_f32 v77, v99, s40, v76
	v_cvt_pk_fp8_f32 v83, v4, v77 op_sel:[0,0,1]
	v_med3_f32 v4, v101, s40, v76
	v_med3_f32 v77, v103, s40, v76
	v_mov_b32_e32 v84, v5
	v_cvt_pk_fp8_f32 v84, v4, v77
	v_med3_f32 v88, v109, s40, v76
	v_med3_f32 v89, v111, s40, v76
	v_mov_b32_e32 v85, v5
	v_cvt_pk_fp8_f32 v85, v88, v89
	v_med3_f32 v4, v105, s40, v76
	v_med3_f32 v77, v107, s40, v76
	v_cvt_pk_fp8_f32 v84, v4, v77 op_sel:[0,0,1]
	v_med3_f32 v4, v113, s40, v76
	v_med3_f32 v77, v115, s40, v76
	v_cvt_pk_fp8_f32 v85, v4, v77 op_sel:[0,0,1]
	v_lshl_add_u64 v[88:89], v[86:87], 0, v[20:21]
	global_store_dwordx4 v[88:89], v[78:81], off nt
	v_readlane_b32 s59, v234, 26
	v_readlane_b32 s62, v234, 29
	v_lshl_add_u64 v[78:79], v[86:87], 0, v[22:23]
	global_store_dwordx4 v[78:79], v[82:85], off nt
	s_waitcnt lgkmcnt(0)
	v_readlane_b32 s63, v234, 30
	v_readlane_b32 s64, v234, 31
	v_readlane_b32 s65, v234, 32
	v_readlane_b32 s66, v234, 33
	v_readlane_b32 s67, v234, 34
	v_readlane_b32 s68, v234, 35
	v_readlane_b32 s69, v234, 36
	v_readlane_b32 s70, v234, 37
	v_readlane_b32 s71, v234, 38

.LBB0_49:
	s_andn2_b64 vcc, exec, s[10:11]
	s_cbranch_vccnz .LBB0_51
	s_and_b32 s0, s9, 0x3fc0
	s_addk_i32 s0, 0xd400
	v_readlane_b32 s56, v234, 7
	s_and_b32 s12, s5, 0x3c0
	s_lshl_b64 s[10:11], s[0:1], 12
	v_readlane_b32 s66, v234, 17
	v_readlane_b32 s67, v234, 18
	s_add_u32 s10, s66, s10
	s_addc_u32 s11, s67, s11
	s_lshl_b32 s13, s12, 2
	s_add_u32 s10, s10, s13
	s_addc_u32 s11, s11, 0
	v_lshl_add_u64 v[78:79], s[10:11], 0, v[66:67]
	v_lshlrev_b32_e32 v4, 2, v2
	v_lshl_add_u64 v[138:139], v[78:79], 0, v[4:5]
	v_add_co_u32_e32 v82, vcc, s21, v138
	v_add_u32_e32 v4, 0x410, v1
	s_nop 0
	v_addc_co_u32_e32 v83, vcc, 0, v139, vcc
	v_add_co_u32_e32 v86, vcc, s24, v138
	global_load_dwordx4 v[78:81], v[138:139], off nt
	s_nop 0
	global_load_dwordx4 v[82:85], v[82:83], off nt
	v_addc_co_u32_e32 v87, vcc, 0, v139, vcc
	v_add_co_u32_e32 v90, vcc, s25, v138
	s_lshl_b32 s10, s12, 11
	s_nop 0
	v_addc_co_u32_e32 v91, vcc, 0, v139, vcc
	global_load_dwordx4 v[86:89], v[86:87], off nt
	s_nop 0
	global_load_dwordx4 v[90:93], v[90:91], off nt
	v_add_co_u32_e32 v94, vcc, s26, v138
	v_readlane_b32 s11, v234, 47
	s_nop 0
	v_addc_co_u32_e32 v95, vcc, 0, v139, vcc
	v_add_co_u32_e32 v98, vcc, s27, v138
	v_add_u32_e32 v77, 0x400, v33
	s_nop 0
	v_addc_co_u32_e32 v99, vcc, 0, v139, vcc
	global_load_dwordx4 v[94:97], v[94:95], off nt
	s_nop 0
	global_load_dwordx4 v[98:101], v[98:99], off nt
	v_add_co_u32_e32 v102, vcc, s28, v138
	s_add_u32 s12, s11, s10
	s_nop 0
	v_addc_co_u32_e32 v103, vcc, 0, v139, vcc
	v_add_co_u32_e32 v106, vcc, s29, v138
	v_readlane_b32 s10, v234, 48
	s_nop 0
	v_addc_co_u32_e32 v107, vcc, 0, v139, vcc
	global_load_dwordx4 v[102:105], v[102:103], off nt
	s_nop 0
	global_load_dwordx4 v[106:109], v[106:107], off nt
	v_add_co_u32_e32 v110, vcc, s30, v138
	s_addc_u32 s13, s10, 0
	s_nop 0
	v_addc_co_u32_e32 v111, vcc, 0, v139, vcc
	v_add_co_u32_e32 v114, vcc, s31, v138
	s_lshl_b64 s[10:11], s[0:1], 1
	s_nop 0
	v_addc_co_u32_e32 v115, vcc, 0, v139, vcc
	global_load_dwordx4 v[110:113], v[110:111], off nt
	s_nop 0
	global_load_dwordx4 v[114:117], v[114:115], off nt
	v_add_co_u32_e32 v118, vcc, s34, v138
	s_add_u32 s10, s12, s10
	s_nop 0
	v_addc_co_u32_e32 v119, vcc, 0, v139, vcc
	v_add_co_u32_e32 v122, vcc, s35, v138
	s_addc_u32 s11, s13, s11
	s_nop 0
	v_addc_co_u32_e32 v123, vcc, 0, v139, vcc
	global_load_dwordx4 v[118:121], v[118:119], off nt
	s_nop 0
	global_load_dwordx4 v[122:125], v[122:123], off nt
	v_add_co_u32_e32 v126, vcc, s36, v138
	v_readlane_b32 s57, v234, 8
	s_nop 0
	v_addc_co_u32_e32 v127, vcc, 0, v139, vcc
	global_load_dwordx4 v[126:129], v[126:127], off nt
	v_add_co_u32_e32 v130, vcc, s37, v138
	v_readlane_b32 s58, v234, 9
	s_nop 0
	v_addc_co_u32_e32 v131, vcc, 0, v139, vcc
	global_load_dwordx4 v[130:133], v[130:131], off nt
	v_add_co_u32_e32 v134, vcc, s38, v138
	v_readlane_b32 s59, v234, 10
	s_nop 0
	v_addc_co_u32_e32 v135, vcc, 0, v139, vcc
	global_load_dwordx4 v[134:137], v[134:135], off nt
	v_add_co_u32_e32 v138, vcc, s39, v138
	v_readlane_b32 s60, v234, 11
	s_nop 0
	v_addc_co_u32_e32 v139, vcc, 0, v139, vcc
	global_load_dwordx4 v[138:141], v[138:139], off nt
	s_waitcnt vmcnt(15)
	ds_write2_b32 v1, v78, v79 offset1:1
	ds_write2_b32 v1, v80, v81 offset0:2 offset1:3
	s_waitcnt vmcnt(14)
	ds_write2_b32 v4, v82, v83 offset1:1
	v_add_u32_e32 v4, 0x418, v1
	ds_write2_b32 v4, v84, v85 offset1:1
	v_add_u32_e32 v4, 0x820, v1
	v_readlane_b32 s61, v234, 12
	v_readlane_b32 s62, v234, 13
	v_readlane_b32 s63, v234, 14
	s_waitcnt vmcnt(13)
	ds_write2_b32 v4, v86, v87 offset1:1
	v_add_u32_e32 v4, 0x828, v1
	ds_write2_b32 v4, v88, v89 offset1:1
	v_add_u32_e32 v4, 0xc30, v1
	s_waitcnt vmcnt(12)
	ds_write2_b32 v4, v90, v91 offset1:1
	v_add_u32_e32 v4, 0xc38, v1
	ds_write2_b32 v4, v92, v93 offset1:1
	v_add_u32_e32 v4, 0x1040, v1
	v_readlane_b32 s64, v234, 15
	v_readlane_b32 s65, v234, 16
	v_readlane_b32 s68, v234, 19
	s_waitcnt vmcnt(11)
	ds_write2_b32 v4, v94, v95 offset1:1
	v_add_u32_e32 v4, 0x1048, v1
	ds_write2_b32 v4, v96, v97 offset1:1
	v_add_u32_e32 v4, 0x1450, v1
	s_waitcnt vmcnt(10)
	ds_write2_b32 v4, v98, v99 offset1:1
	v_add_u32_e32 v4, 0x1458, v1
	ds_write2_b32 v4, v100, v101 offset1:1
	v_add_u32_e32 v4, 0x1860, v1
	v_readlane_b32 s69, v234, 20
	v_readlane_b32 s70, v234, 21
	v_readlane_b32 s71, v234, 22
	s_waitcnt vmcnt(9)
	ds_write2_b32 v4, v102, v103 offset1:1
	v_add_u32_e32 v4, 0x1868, v1
	ds_write2_b32 v4, v104, v105 offset1:1
	v_add_u32_e32 v4, 0x1c70, v1
	s_waitcnt vmcnt(8)
	ds_write2_b32 v4, v106, v107 offset1:1
	v_add_u32_e32 v4, 0x1c78, v1
	ds_write2_b32 v4, v108, v109 offset1:1
	v_add_u32_e32 v4, 0x2080, v1
	s_waitcnt vmcnt(7)
	ds_write2_b32 v4, v110, v111 offset1:1
	v_add_u32_e32 v4, 0x2088, v1
	ds_write2_b32 v4, v112, v113 offset1:1
	v_add_u32_e32 v4, 0x2490, v1
	s_waitcnt vmcnt(6)
	ds_write2_b32 v4, v114, v115 offset1:1
	v_add_u32_e32 v4, 0x2498, v1
	ds_write2_b32 v4, v116, v117 offset1:1
	v_add_u32_e32 v4, 0x28a0, v1
	s_waitcnt vmcnt(5)
	ds_write2_b32 v4, v118, v119 offset1:1
	v_add_u32_e32 v4, 0x28a8, v1
	ds_write2_b32 v4, v120, v121 offset1:1
	v_add_u32_e32 v4, 0x2cb0, v1
	s_waitcnt vmcnt(4)
	ds_write2_b32 v4, v122, v123 offset1:1
	v_add_u32_e32 v4, 0x2cb8, v1
	ds_write2_b32 v4, v124, v125 offset1:1
	v_add_u32_e32 v4, 0x30c0, v1
	s_waitcnt vmcnt(3)
	ds_write2_b32 v4, v126, v127 offset1:1
	v_add_u32_e32 v4, 0x30c8, v1
	ds_write2_b32 v4, v128, v129 offset1:1
	v_add_u32_e32 v4, 0x34d0, v1
	s_waitcnt vmcnt(2)
	ds_write2_b32 v4, v130, v131 offset1:1
	v_add_u32_e32 v4, 0x34d8, v1
	ds_write2_b32 v4, v132, v133 offset1:1
	v_add_u32_e32 v4, 0x38e0, v1
	s_waitcnt vmcnt(1)
	ds_write2_b32 v4, v134, v135 offset1:1
	v_add_u32_e32 v4, 0x38e8, v1
	ds_write2_b32 v4, v136, v137 offset1:1
	v_add_u32_e32 v4, 0x3cf0, v1
	s_waitcnt vmcnt(0)
	ds_write2_b32 v4, v138, v139 offset1:1
	v_add_u32_e32 v4, 0x3cf8, v1
	ds_write2_b32 v4, v140, v141 offset1:1
	s_waitcnt lgkmcnt(0)
	ds_read2_b32 v[82:83], v33 offset0:65 offset1:73
	ds_read2_b32 v[84:85], v33 offset1:8
	ds_read2_b32 v[86:87], v33 offset0:130 offset1:138
	ds_read2_b32 v[88:89], v33 offset0:195 offset1:203
	ds_read2_b32 v[90:91], v77 offset0:4 offset1:12
	ds_read2_b32 v[92:93], v77 offset0:69 offset1:77
	ds_read2_b32 v[94:95], v77 offset0:134 offset1:142
	ds_read2_b32 v[96:97], v77 offset0:199 offset1:207
	v_lshlrev_b32_e32 v4, 1, v32
	v_lshl_add_u64 v[98:99], s[10:11], 0, v[4:5]
	s_waitcnt lgkmcnt(6)
	v_cvt_pk_bf16_f32 v78, v84, v82
	s_waitcnt lgkmcnt(4)
	v_cvt_pk_bf16_f32 v79, v86, v88
	s_waitcnt lgkmcnt(2)
	v_cvt_pk_bf16_f32 v80, v90, v92
	s_waitcnt lgkmcnt(0)
	v_cvt_pk_bf16_f32 v81, v94, v96
	v_lshl_add_u64 v[100:101], v[98:99], 0, v[34:35]
	global_store_dwordx4 v[100:101], v[78:81], off nt
	s_nop 1
	v_cvt_pk_bf16_f32 v78, v85, v83
	v_cvt_pk_bf16_f32 v79, v87, v89
	v_cvt_pk_bf16_f32 v80, v91, v93
	v_cvt_pk_bf16_f32 v81, v95, v97
	ds_read2_b32 v[84:85], v33 offset0:81 offset1:89
	ds_read2_b32 v[86:87], v33 offset0:16 offset1:24
	ds_read2_b32 v[88:89], v33 offset0:146 offset1:154
	ds_read2_b32 v[90:91], v33 offset0:211 offset1:219
	ds_read2_b32 v[92:93], v77 offset0:20 offset1:28
	ds_read2_b32 v[94:95], v77 offset0:85 offset1:93
	ds_read2_b32 v[96:97], v77 offset0:150 offset1:158
	ds_read2_b32 v[100:101], v77 offset0:215 offset1:223
	v_lshl_add_u64 v[82:83], v[98:99], 0, v[36:37]
	global_store_dwordx4 v[82:83], v[78:81], off nt
	v_lshl_add_u64 v[82:83], v[98:99], 0, v[38:39]
	s_waitcnt lgkmcnt(6)
	v_cvt_pk_bf16_f32 v78, v86, v84
	s_waitcnt lgkmcnt(4)
	v_cvt_pk_bf16_f32 v79, v88, v90
	s_waitcnt lgkmcnt(2)
	v_cvt_pk_bf16_f32 v80, v92, v94
	s_waitcnt lgkmcnt(0)
	v_cvt_pk_bf16_f32 v81, v96, v100
	global_store_dwordx4 v[82:83], v[78:81], off nt
	v_lshl_add_u64 v[82:83], v[98:99], 0, v[46:47]
	s_nop 0
	v_cvt_pk_bf16_f32 v78, v87, v85
	v_cvt_pk_bf16_f32 v79, v89, v91
	v_cvt_pk_bf16_f32 v80, v93, v95
	v_cvt_pk_bf16_f32 v81, v97, v101
	ds_read2_b32 v[84:85], v33 offset0:32 offset1:40
	ds_read2_b32 v[86:87], v33 offset0:97 offset1:105
	ds_read2_b32 v[88:89], v33 offset0:162 offset1:170
	ds_read2_b32 v[90:91], v33 offset0:227 offset1:235
	ds_read2_b32 v[92:93], v77 offset0:36 offset1:44
	ds_read2_b32 v[94:95], v77 offset0:101 offset1:109
	ds_read2_b32 v[96:97], v77 offset0:166 offset1:174
	ds_read2_b32 v[100:101], v77 offset0:231 offset1:239
	global_store_dwordx4 v[82:83], v[78:81], off nt
	v_lshl_add_u64 v[82:83], v[98:99], 0, v[50:51]
	s_waitcnt lgkmcnt(6)
	v_cvt_pk_bf16_f32 v78, v84, v86
	s_waitcnt lgkmcnt(4)
	v_cvt_pk_bf16_f32 v79, v88, v90
	s_waitcnt lgkmcnt(2)
	v_cvt_pk_bf16_f32 v80, v92, v94
	s_waitcnt lgkmcnt(0)
	v_cvt_pk_bf16_f32 v81, v96, v100
	global_store_dwordx4 v[82:83], v[78:81], off nt
	v_lshl_add_u64 v[82:83], v[98:99], 0, v[54:55]
	s_nop 0
	v_cvt_pk_bf16_f32 v78, v85, v87
	v_cvt_pk_bf16_f32 v79, v89, v91
	v_cvt_pk_bf16_f32 v80, v93, v95
	v_cvt_pk_bf16_f32 v81, v97, v101
	ds_read2_b32 v[84:85], v33 offset0:48 offset1:56
	ds_read2_b32 v[86:87], v33 offset0:113 offset1:121
	ds_read2_b32 v[88:89], v33 offset0:178 offset1:186
	ds_read2_b32 v[90:91], v33 offset0:243 offset1:251
	ds_read2_b32 v[92:93], v77 offset0:52 offset1:60
	ds_read2_b32 v[94:95], v77 offset0:117 offset1:125
	ds_read2_b32 v[96:97], v77 offset0:182 offset1:190
	ds_read2_b32 v[100:101], v77 offset0:247 offset1:255
	global_store_dwordx4 v[82:83], v[78:81], off nt
	v_lshl_add_u64 v[82:83], v[98:99], 0, v[58:59]
	s_waitcnt lgkmcnt(6)
	v_cvt_pk_bf16_f32 v78, v84, v86
	s_waitcnt lgkmcnt(4)
	v_cvt_pk_bf16_f32 v79, v88, v90
	s_waitcnt lgkmcnt(2)
	v_cvt_pk_bf16_f32 v80, v92, v94
	s_waitcnt lgkmcnt(0)
	v_cvt_pk_bf16_f32 v81, v96, v100
	global_store_dwordx4 v[82:83], v[78:81], off nt
	v_lshl_add_u64 v[82:83], v[98:99], 0, v[62:63]
	s_nop 0
	v_cvt_pk_bf16_f32 v78, v85, v87
	v_cvt_pk_bf16_f32 v79, v89, v91
	v_cvt_pk_bf16_f32 v80, v93, v95
	v_cvt_pk_bf16_f32 v81, v97, v101
	global_store_dwordx4 v[82:83], v[78:81], off nt
	s_waitcnt lgkmcnt(0)

.LBB0_52:
	s_andn2_b64 vcc, exec, s[10:11]
	s_cbranch_vccnz .LBB0_54
	s_and_b32 s0, s9, 0x3fc0
	s_addk_i32 s0, 0xd800
	v_readlane_b32 s56, v234, 7
	s_and_b32 s12, s5, 0x3c0
	s_lshl_b64 s[10:11], s[0:1], 12
	v_readlane_b32 s64, v234, 15
	v_readlane_b32 s65, v234, 16
	s_add_u32 s10, s64, s10
	s_addc_u32 s11, s65, s11
	s_lshl_b32 s13, s12, 2
	s_add_u32 s10, s10, s13
	s_addc_u32 s11, s11, 0
	v_lshl_add_u64 v[78:79], s[10:11], 0, v[66:67]
	v_lshlrev_b32_e32 v4, 2, v2
	v_lshl_add_u64 v[134:135], v[78:79], 0, v[4:5]
	v_add_co_u32_e32 v82, vcc, s21, v134
	global_load_dwordx4 v[78:81], v[134:135], off nt
	s_nop 0
	v_addc_co_u32_e32 v83, vcc, 0, v135, vcc
	v_add_co_u32_e32 v86, vcc, s24, v134
	global_load_dwordx4 v[82:85], v[82:83], off nt
	s_nop 0
	v_addc_co_u32_e32 v87, vcc, 0, v135, vcc
	v_add_co_u32_e32 v90, vcc, s25, v134
	global_load_dwordx4 v[86:89], v[86:87], off nt
	s_nop 0
	v_addc_co_u32_e32 v91, vcc, 0, v135, vcc
	v_add_co_u32_e32 v94, vcc, s26, v134
	global_load_dwordx4 v[90:93], v[90:91], off nt
	s_nop 0
	v_addc_co_u32_e32 v95, vcc, 0, v135, vcc
	v_add_co_u32_e32 v98, vcc, s27, v134
	global_load_dwordx4 v[94:97], v[94:95], off nt
	s_nop 0
	v_addc_co_u32_e32 v99, vcc, 0, v135, vcc
	v_add_co_u32_e32 v102, vcc, s28, v134
	global_load_dwordx4 v[98:101], v[98:99], off nt
	s_nop 0
	v_addc_co_u32_e32 v103, vcc, 0, v135, vcc
	v_add_co_u32_e32 v106, vcc, s29, v134
	global_load_dwordx4 v[102:105], v[102:103], off nt
	s_nop 0
	v_addc_co_u32_e32 v107, vcc, 0, v135, vcc
	v_add_co_u32_e32 v110, vcc, s30, v134
	global_load_dwordx4 v[106:109], v[106:107], off nt
	s_nop 0
	v_addc_co_u32_e32 v111, vcc, 0, v135, vcc
	v_add_co_u32_e32 v114, vcc, s31, v134
	global_load_dwordx4 v[110:113], v[110:111], off nt
	s_nop 0
	v_addc_co_u32_e32 v115, vcc, 0, v135, vcc
	v_add_co_u32_e32 v118, vcc, s34, v134
	global_load_dwordx4 v[114:117], v[114:115], off nt
	s_nop 0
	v_addc_co_u32_e32 v119, vcc, 0, v135, vcc
	v_add_co_u32_e32 v122, vcc, s35, v134
	v_add_u32_e32 v4, 0x410, v1
	s_nop 0
	v_addc_co_u32_e32 v123, vcc, 0, v135, vcc
	global_load_dwordx4 v[118:121], v[118:119], off nt
	s_nop 0
	global_load_dwordx4 v[122:125], v[122:123], off nt
	v_add_co_u32_e32 v126, vcc, s36, v134
	s_lshl_b32 s12, s12, 11
	s_nop 0
	v_addc_co_u32_e32 v127, vcc, 0, v135, vcc
	v_add_co_u32_e32 v130, vcc, s37, v134
	s_add_u32 s12, s84, s12
	s_nop 0
	v_addc_co_u32_e32 v131, vcc, 0, v135, vcc
	global_load_dwordx4 v[126:129], v[126:127], off nt
	s_nop 0
	global_load_dwordx4 v[130:133], v[130:131], off nt
	v_add_co_u32_e32 v136, vcc, s38, v134
	s_addc_u32 s13, s85, 0
	s_nop 0
	v_addc_co_u32_e32 v137, vcc, 0, v135, vcc
	v_add_co_u32_e32 v138, vcc, s39, v134
	s_lshl_b64 s[10:11], s[0:1], 1
	s_nop 0
	v_addc_co_u32_e32 v139, vcc, 0, v135, vcc
	global_load_dwordx4 v[134:137], v[136:137], off nt
	s_nop 0
	global_load_dwordx4 v[138:141], v[138:139], off nt
	s_add_u32 s10, s12, s10
	s_addc_u32 s11, s13, s11
	v_readlane_b32 s57, v234, 8
	v_readlane_b32 s58, v234, 9
	s_waitcnt vmcnt(15)
	v_pk_mul_f32 v[78:79], v[78:79], s[8:9] op_sel_hi:[1,0]
	ds_write2_b32 v1, v78, v79 offset1:1
	v_pk_mul_f32 v[78:79], v[80:81], s[8:9] op_sel_hi:[1,0]
	ds_write2_b32 v1, v78, v79 offset0:2 offset1:3
	v_readlane_b32 s59, v234, 10
	s_waitcnt vmcnt(14)
	v_pk_mul_f32 v[78:79], v[82:83], s[8:9] op_sel_hi:[1,0]
	ds_write2_b32 v4, v78, v79 offset1:1
	v_pk_mul_f32 v[78:79], v[84:85], s[8:9] op_sel_hi:[1,0]
	v_add_u32_e32 v4, 0x418, v1
	ds_write2_b32 v4, v78, v79 offset1:1
	s_waitcnt vmcnt(13)
	v_pk_mul_f32 v[78:79], v[86:87], s[8:9] op_sel_hi:[1,0]
	v_add_u32_e32 v4, 0x820, v1
	ds_write2_b32 v4, v78, v79 offset1:1
	v_pk_mul_f32 v[78:79], v[88:89], s[8:9] op_sel_hi:[1,0]
	v_add_u32_e32 v4, 0x828, v1
	ds_write2_b32 v4, v78, v79 offset1:1
	s_waitcnt vmcnt(12)
	v_pk_mul_f32 v[78:79], v[90:91], s[8:9] op_sel_hi:[1,0]
	v_add_u32_e32 v4, 0xc30, v1
	ds_write2_b32 v4, v78, v79 offset1:1
	v_pk_mul_f32 v[78:79], v[92:93], s[8:9] op_sel_hi:[1,0]
	v_add_u32_e32 v4, 0xc38, v1
	ds_write2_b32 v4, v78, v79 offset1:1
	s_waitcnt vmcnt(11)
	v_pk_mul_f32 v[78:79], v[94:95], s[8:9] op_sel_hi:[1,0]
	v_add_u32_e32 v4, 0x1040, v1
	ds_write2_b32 v4, v78, v79 offset1:1
	v_pk_mul_f32 v[78:79], v[96:97], s[8:9] op_sel_hi:[1,0]
	v_add_u32_e32 v4, 0x1048, v1
	ds_write2_b32 v4, v78, v79 offset1:1
	s_waitcnt vmcnt(10)
	v_pk_mul_f32 v[78:79], v[98:99], s[8:9] op_sel_hi:[1,0]
	v_add_u32_e32 v4, 0x1450, v1
	ds_write2_b32 v4, v78, v79 offset1:1
	v_pk_mul_f32 v[78:79], v[100:101], s[8:9] op_sel_hi:[1,0]
	v_add_u32_e32 v4, 0x1458, v1
	ds_write2_b32 v4, v78, v79 offset1:1
	s_waitcnt vmcnt(9)
	v_pk_mul_f32 v[78:79], v[102:103], s[8:9] op_sel_hi:[1,0]
	v_add_u32_e32 v4, 0x1860, v1
	ds_write2_b32 v4, v78, v79 offset1:1
	v_pk_mul_f32 v[78:79], v[104:105], s[8:9] op_sel_hi:[1,0]
	v_add_u32_e32 v4, 0x1868, v1
	ds_write2_b32 v4, v78, v79 offset1:1
	s_waitcnt vmcnt(8)
	v_pk_mul_f32 v[78:79], v[106:107], s[8:9] op_sel_hi:[1,0]
	v_add_u32_e32 v4, 0x1c70, v1
	ds_write2_b32 v4, v78, v79 offset1:1
	v_pk_mul_f32 v[78:79], v[108:109], s[8:9] op_sel_hi:[1,0]
	v_add_u32_e32 v4, 0x1c78, v1
	ds_write2_b32 v4, v78, v79 offset1:1
	s_waitcnt vmcnt(7)
	v_pk_mul_f32 v[78:79], v[110:111], s[8:9] op_sel_hi:[1,0]
	v_add_u32_e32 v4, 0x2080, v1
	ds_write2_b32 v4, v78, v79 offset1:1
	v_pk_mul_f32 v[78:79], v[112:113], s[8:9] op_sel_hi:[1,0]
	v_add_u32_e32 v4, 0x2088, v1
	ds_write2_b32 v4, v78, v79 offset1:1
	s_waitcnt vmcnt(6)
	v_pk_mul_f32 v[78:79], v[114:115], s[8:9] op_sel_hi:[1,0]
	v_add_u32_e32 v4, 0x2490, v1
	ds_write2_b32 v4, v78, v79 offset1:1
	v_pk_mul_f32 v[78:79], v[116:117], s[8:9] op_sel_hi:[1,0]
	v_add_u32_e32 v4, 0x2498, v1
	ds_write2_b32 v4, v78, v79 offset1:1
	s_waitcnt vmcnt(5)
	v_pk_mul_f32 v[78:79], v[118:119], s[8:9] op_sel_hi:[1,0]
	v_add_u32_e32 v4, 0x28a0, v1
	ds_write2_b32 v4, v78, v79 offset1:1
	v_pk_mul_f32 v[78:79], v[120:121], s[8:9] op_sel_hi:[1,0]
	v_add_u32_e32 v4, 0x28a8, v1
	ds_write2_b32 v4, v78, v79 offset1:1
	s_waitcnt vmcnt(4)
	v_pk_mul_f32 v[78:79], v[122:123], s[8:9] op_sel_hi:[1,0]
	v_add_u32_e32 v4, 0x2cb0, v1
	ds_write2_b32 v4, v78, v79 offset1:1
	v_pk_mul_f32 v[78:79], v[124:125], s[8:9] op_sel_hi:[1,0]
	v_add_u32_e32 v4, 0x2cb8, v1
	ds_write2_b32 v4, v78, v79 offset1:1
	s_waitcnt vmcnt(3)
	v_pk_mul_f32 v[78:79], v[126:127], s[8:9] op_sel_hi:[1,0]
	v_add_u32_e32 v4, 0x30c0, v1
	ds_write2_b32 v4, v78, v79 offset1:1
	v_pk_mul_f32 v[78:79], v[128:129], s[8:9] op_sel_hi:[1,0]
	v_add_u32_e32 v4, 0x30c8, v1
	ds_write2_b32 v4, v78, v79 offset1:1
	s_waitcnt vmcnt(2)
	v_pk_mul_f32 v[78:79], v[130:131], s[8:9] op_sel_hi:[1,0]
	v_add_u32_e32 v4, 0x34d0, v1
	ds_write2_b32 v4, v78, v79 offset1:1
	v_pk_mul_f32 v[78:79], v[132:133], s[8:9] op_sel_hi:[1,0]
	v_add_u32_e32 v4, 0x34d8, v1
	ds_write2_b32 v4, v78, v79 offset1:1
	s_waitcnt vmcnt(1)
	v_pk_mul_f32 v[78:79], v[134:135], s[8:9] op_sel_hi:[1,0]
	v_add_u32_e32 v4, 0x38e0, v1
	ds_write2_b32 v4, v78, v79 offset1:1
	v_pk_mul_f32 v[78:79], v[136:137], s[8:9] op_sel_hi:[1,0]
	v_add_u32_e32 v4, 0x38e8, v1
	ds_write2_b32 v4, v78, v79 offset1:1
	s_waitcnt vmcnt(0)
	v_pk_mul_f32 v[78:79], v[138:139], s[8:9] op_sel_hi:[1,0]
	v_add_u32_e32 v4, 0x3cf0, v1
	ds_write2_b32 v4, v78, v79 offset1:1
	v_pk_mul_f32 v[78:79], v[140:141], s[8:9] op_sel_hi:[1,0]
	v_add_u32_e32 v4, 0x3cf8, v1
	ds_write2_b32 v4, v78, v79 offset1:1
	v_lshlrev_b32_e32 v4, 1, v32
	s_waitcnt lgkmcnt(0)
	v_lshl_add_u64 v[78:79], s[10:11], 0, v[4:5]
	v_add_u32_e32 v4, 0x400, v33
	ds_read2_b32 v[82:83], v33 offset0:65 offset1:73
	ds_read2_b32 v[84:85], v33 offset1:8
	ds_read2_b32 v[86:87], v33 offset0:130 offset1:138
	ds_read2_b32 v[88:89], v33 offset0:195 offset1:203
	ds_read2_b32 v[90:91], v4 offset0:4 offset1:12
	ds_read2_b32 v[92:93], v4 offset0:69 offset1:77
	ds_read2_b32 v[94:95], v4 offset0:134 offset1:142
	ds_read2_b32 v[96:97], v4 offset0:199 offset1:207
	s_mov_b64 s[10:11], 0x2400000
	v_lshl_add_u64 v[98:99], v[78:79], 0, s[10:11]
	s_waitcnt lgkmcnt(6)
	v_cvt_pk_bf16_f32 v78, v84, v82
	s_waitcnt lgkmcnt(4)
	v_cvt_pk_bf16_f32 v79, v86, v88
	s_waitcnt lgkmcnt(2)
	v_cvt_pk_bf16_f32 v80, v90, v92
	s_waitcnt lgkmcnt(0)
	v_cvt_pk_bf16_f32 v81, v94, v96
	v_lshl_add_u64 v[100:101], v[98:99], 0, v[34:35]
	global_store_dwordx4 v[100:101], v[78:81], off nt
	v_readlane_b32 s60, v234, 11
	v_readlane_b32 s61, v234, 12
	v_cvt_pk_bf16_f32 v78, v85, v83
	v_cvt_pk_bf16_f32 v79, v87, v89
	v_cvt_pk_bf16_f32 v80, v91, v93
	v_cvt_pk_bf16_f32 v81, v95, v97
	ds_read2_b32 v[84:85], v33 offset0:81 offset1:89
	ds_read2_b32 v[86:87], v33 offset0:16 offset1:24
	ds_read2_b32 v[88:89], v33 offset0:146 offset1:154
	ds_read2_b32 v[90:91], v33 offset0:211 offset1:219
	ds_read2_b32 v[92:93], v4 offset0:20 offset1:28
	ds_read2_b32 v[94:95], v4 offset0:85 offset1:93
	ds_read2_b32 v[96:97], v4 offset0:150 offset1:158
	ds_read2_b32 v[100:101], v4 offset0:215 offset1:223
	v_lshl_add_u64 v[82:83], v[98:99], 0, v[36:37]
	global_store_dwordx4 v[82:83], v[78:81], off nt
	v_lshl_add_u64 v[82:83], v[98:99], 0, v[38:39]
	v_readlane_b32 s62, v234, 13
	s_waitcnt lgkmcnt(6)
	v_cvt_pk_bf16_f32 v78, v86, v84
	s_waitcnt lgkmcnt(4)
	v_cvt_pk_bf16_f32 v79, v88, v90
	s_waitcnt lgkmcnt(2)
	v_cvt_pk_bf16_f32 v80, v92, v94
	s_waitcnt lgkmcnt(0)
	v_cvt_pk_bf16_f32 v81, v96, v100
	global_store_dwordx4 v[82:83], v[78:81], off nt
	v_lshl_add_u64 v[82:83], v[98:99], 0, v[46:47]
	v_readlane_b32 s63, v234, 14
	v_cvt_pk_bf16_f32 v78, v87, v85
	v_cvt_pk_bf16_f32 v79, v89, v91
	v_cvt_pk_bf16_f32 v80, v93, v95
	v_cvt_pk_bf16_f32 v81, v97, v101
	ds_read2_b32 v[84:85], v33 offset0:32 offset1:40
	ds_read2_b32 v[86:87], v33 offset0:97 offset1:105
	ds_read2_b32 v[88:89], v33 offset0:162 offset1:170
	ds_read2_b32 v[90:91], v33 offset0:227 offset1:235
	ds_read2_b32 v[92:93], v4 offset0:36 offset1:44
	ds_read2_b32 v[94:95], v4 offset0:101 offset1:109
	ds_read2_b32 v[96:97], v4 offset0:166 offset1:174
	ds_read2_b32 v[100:101], v4 offset0:231 offset1:239
	global_store_dwordx4 v[82:83], v[78:81], off nt
	v_lshl_add_u64 v[82:83], v[98:99], 0, v[50:51]
	v_readlane_b32 s66, v234, 17
	s_waitcnt lgkmcnt(6)
	v_cvt_pk_bf16_f32 v78, v84, v86
	s_waitcnt lgkmcnt(4)
	v_cvt_pk_bf16_f32 v79, v88, v90
	s_waitcnt lgkmcnt(2)
	v_cvt_pk_bf16_f32 v80, v92, v94
	s_waitcnt lgkmcnt(0)
	v_cvt_pk_bf16_f32 v81, v96, v100
	global_store_dwordx4 v[82:83], v[78:81], off nt
	v_lshl_add_u64 v[82:83], v[98:99], 0, v[54:55]
	v_readlane_b32 s67, v234, 18
	v_cvt_pk_bf16_f32 v78, v85, v87
	v_cvt_pk_bf16_f32 v79, v89, v91
	v_cvt_pk_bf16_f32 v80, v93, v95
	v_cvt_pk_bf16_f32 v81, v97, v101
	ds_read2_b32 v[84:85], v33 offset0:48 offset1:56
	ds_read2_b32 v[86:87], v33 offset0:113 offset1:121
	ds_read2_b32 v[88:89], v33 offset0:178 offset1:186
	ds_read2_b32 v[90:91], v33 offset0:243 offset1:251
	ds_read2_b32 v[92:93], v4 offset0:52 offset1:60
	ds_read2_b32 v[94:95], v4 offset0:117 offset1:125
	ds_read2_b32 v[96:97], v4 offset0:182 offset1:190
	ds_read2_b32 v[100:101], v4 offset0:247 offset1:255
	global_store_dwordx4 v[82:83], v[78:81], off nt
	v_lshl_add_u64 v[82:83], v[98:99], 0, v[58:59]
	v_readlane_b32 s68, v234, 19
	s_waitcnt lgkmcnt(6)
	v_cvt_pk_bf16_f32 v78, v84, v86
	s_waitcnt lgkmcnt(4)
	v_cvt_pk_bf16_f32 v79, v88, v90
	s_waitcnt lgkmcnt(2)
	v_cvt_pk_bf16_f32 v80, v92, v94
	s_waitcnt lgkmcnt(0)
	v_cvt_pk_bf16_f32 v81, v96, v100
	global_store_dwordx4 v[82:83], v[78:81], off nt
	v_lshl_add_u64 v[82:83], v[98:99], 0, v[62:63]
	v_readlane_b32 s69, v234, 20
	v_cvt_pk_bf16_f32 v78, v85, v87
	v_cvt_pk_bf16_f32 v79, v89, v91
	v_cvt_pk_bf16_f32 v80, v93, v95
	v_cvt_pk_bf16_f32 v81, v97, v101
	global_store_dwordx4 v[82:83], v[78:81], off nt
	s_waitcnt lgkmcnt(0)
	v_readlane_b32 s70, v234, 21
	v_readlane_b32 s71, v234, 22

.LBB0_60:
	s_and_b32 s0, s19, 0x1fc0
	s_addk_i32 s0, 0xf000
	s_lshl_b64 s[12:13], s[0:1], 1
	s_add_u32 s10, s10, s12
	v_readlane_b32 s56, v234, 7
	s_addc_u32 s11, s11, s13
	s_lshl_b64 s[12:13], s[0:1], 13
	v_readlane_b32 s62, v234, 13
	v_readlane_b32 s63, v234, 14
	s_add_u32 s0, s62, s12
	s_addc_u32 s13, s63, s13
	s_lshl_b32 s12, s14, 2
	s_add_u32 s12, s0, s12
	s_addc_u32 s13, s13, 0
	v_lshl_add_u64 v[78:79], s[12:13], 0, v[72:73]
	v_lshlrev_b32_e32 v4, 2, v2
	v_lshl_add_u64 v[138:139], v[78:79], 0, v[4:5]
	v_add_co_u32_e32 v82, vcc, s24, v138
	s_mov_b32 s0, 0x40000
	s_nop 0
	v_addc_co_u32_e32 v83, vcc, 0, v139, vcc
	v_add_co_u32_e32 v86, vcc, s26, v138
	global_load_dwordx4 v[78:81], v[138:139], off nt
	s_nop 0
	global_load_dwordx4 v[82:85], v[82:83], off nt
	v_addc_co_u32_e32 v87, vcc, 0, v139, vcc
	v_add_co_u32_e32 v90, vcc, s28, v138
	v_add_u32_e32 v4, 0x410, v1
	s_nop 0
	v_addc_co_u32_e32 v91, vcc, 0, v139, vcc
	global_load_dwordx4 v[86:89], v[86:87], off nt
	s_nop 0
	global_load_dwordx4 v[90:93], v[90:91], off nt
	v_add_co_u32_e32 v94, vcc, s30, v138
	v_add_u32_e32 v77, 0x400, v33
	s_nop 0
	v_addc_co_u32_e32 v95, vcc, 0, v139, vcc
	v_add_co_u32_e32 v98, vcc, s34, v138
	v_readlane_b32 s57, v234, 8
	s_nop 0
	v_addc_co_u32_e32 v99, vcc, 0, v139, vcc
	global_load_dwordx4 v[94:97], v[94:95], off nt
	s_nop 0
	global_load_dwordx4 v[98:101], v[98:99], off nt
	v_add_co_u32_e32 v102, vcc, s36, v138
	v_readlane_b32 s58, v234, 9
	s_nop 0
	v_addc_co_u32_e32 v103, vcc, 0, v139, vcc
	v_add_co_u32_e32 v106, vcc, s38, v138
	v_readlane_b32 s59, v234, 10
	s_nop 0
	v_addc_co_u32_e32 v107, vcc, 0, v139, vcc
	global_load_dwordx4 v[102:105], v[102:103], off nt
	s_nop 0
	global_load_dwordx4 v[106:109], v[106:107], off nt
	v_add_co_u32_e32 v110, vcc, s0, v138
	s_mov_b32 s0, 0x50000
	s_nop 0
	v_addc_co_u32_e32 v111, vcc, 0, v139, vcc
	v_add_co_u32_e32 v114, vcc, s49, v138
	v_readlane_b32 s60, v234, 11
	s_nop 0
	v_addc_co_u32_e32 v115, vcc, 0, v139, vcc
	global_load_dwordx4 v[110:113], v[110:111], off nt
	s_nop 0
	global_load_dwordx4 v[114:117], v[114:115], off nt
	v_add_co_u32_e32 v118, vcc, s0, v138
	s_mov_b32 s0, 0x68000
	s_nop 0
	v_addc_co_u32_e32 v119, vcc, 0, v139, vcc
	v_add_co_u32_e32 v122, vcc, s45, v138
	v_readlane_b32 s61, v234, 12
	s_nop 0
	v_addc_co_u32_e32 v123, vcc, 0, v139, vcc
	global_load_dwordx4 v[118:121], v[118:119], off nt
	s_nop 0
	global_load_dwordx4 v[122:125], v[122:123], off nt
	v_add_co_u32_e32 v126, vcc, s50, v138
	v_readlane_b32 s64, v234, 15
	s_nop 0
	v_addc_co_u32_e32 v127, vcc, 0, v139, vcc
	global_load_dwordx4 v[126:129], v[126:127], off nt
	v_add_co_u32_e32 v130, vcc, s0, v138
	v_readlane_b32 s65, v234, 16
	s_nop 0
	v_addc_co_u32_e32 v131, vcc, 0, v139, vcc
	global_load_dwordx4 v[130:133], v[130:131], off nt
	v_add_co_u32_e32 v134, vcc, s41, v138
	v_readlane_b32 s66, v234, 17
	s_nop 0
	v_addc_co_u32_e32 v135, vcc, 0, v139, vcc
	global_load_dwordx4 v[134:137], v[134:135], off nt
	v_add_co_u32_e32 v138, vcc, s51, v138
	v_readlane_b32 s67, v234, 18
	s_nop 0
	v_addc_co_u32_e32 v139, vcc, 0, v139, vcc
	global_load_dwordx4 v[138:141], v[138:139], off nt
	s_waitcnt vmcnt(15)
	ds_write2_b32 v1, v78, v79 offset1:1
	ds_write2_b32 v1, v80, v81 offset0:2 offset1:3
	s_waitcnt vmcnt(14)
	ds_write2_b32 v4, v82, v83 offset1:1
	v_add_u32_e32 v4, 0x418, v1
	ds_write2_b32 v4, v84, v85 offset1:1
	v_add_u32_e32 v4, 0x820, v1
	v_readlane_b32 s68, v234, 19
	v_readlane_b32 s69, v234, 20
	v_readlane_b32 s70, v234, 21
	s_waitcnt vmcnt(13)
	ds_write2_b32 v4, v86, v87 offset1:1
	v_add_u32_e32 v4, 0x828, v1
	ds_write2_b32 v4, v88, v89 offset1:1
	v_add_u32_e32 v4, 0xc30, v1
	s_waitcnt vmcnt(12)
	ds_write2_b32 v4, v90, v91 offset1:1
	v_add_u32_e32 v4, 0xc38, v1
	ds_write2_b32 v4, v92, v93 offset1:1
	v_add_u32_e32 v4, 0x1040, v1
	v_readlane_b32 s71, v234, 22
	s_waitcnt vmcnt(11)
	ds_write2_b32 v4, v94, v95 offset1:1
	v_add_u32_e32 v4, 0x1048, v1
	ds_write2_b32 v4, v96, v97 offset1:1
	v_add_u32_e32 v4, 0x1450, v1
	s_waitcnt vmcnt(10)
	ds_write2_b32 v4, v98, v99 offset1:1
	v_add_u32_e32 v4, 0x1458, v1
	ds_write2_b32 v4, v100, v101 offset1:1
	v_add_u32_e32 v4, 0x1860, v1
	s_waitcnt vmcnt(9)
	ds_write2_b32 v4, v102, v103 offset1:1
	v_add_u32_e32 v4, 0x1868, v1
	ds_write2_b32 v4, v104, v105 offset1:1
	v_add_u32_e32 v4, 0x1c70, v1
	s_waitcnt vmcnt(8)
	ds_write2_b32 v4, v106, v107 offset1:1
	v_add_u32_e32 v4, 0x1c78, v1
	ds_write2_b32 v4, v108, v109 offset1:1
	v_add_u32_e32 v4, 0x2080, v1
	s_waitcnt vmcnt(7)
	ds_write2_b32 v4, v110, v111 offset1:1
	v_add_u32_e32 v4, 0x2088, v1
	ds_write2_b32 v4, v112, v113 offset1:1
	v_add_u32_e32 v4, 0x2490, v1
	s_waitcnt vmcnt(6)
	ds_write2_b32 v4, v114, v115 offset1:1
	v_add_u32_e32 v4, 0x2498, v1
	ds_write2_b32 v4, v116, v117 offset1:1
	v_add_u32_e32 v4, 0x28a0, v1
	s_waitcnt vmcnt(5)
	ds_write2_b32 v4, v118, v119 offset1:1
	v_add_u32_e32 v4, 0x28a8, v1
	ds_write2_b32 v4, v120, v121 offset1:1
	v_add_u32_e32 v4, 0x2cb0, v1
	s_waitcnt vmcnt(4)
	ds_write2_b32 v4, v122, v123 offset1:1
	v_add_u32_e32 v4, 0x2cb8, v1
	ds_write2_b32 v4, v124, v125 offset1:1
	v_add_u32_e32 v4, 0x30c0, v1
	s_waitcnt vmcnt(3)
	ds_write2_b32 v4, v126, v127 offset1:1
	v_add_u32_e32 v4, 0x30c8, v1
	ds_write2_b32 v4, v128, v129 offset1:1
	v_add_u32_e32 v4, 0x34d0, v1
	s_waitcnt vmcnt(2)
	ds_write2_b32 v4, v130, v131 offset1:1
	v_add_u32_e32 v4, 0x34d8, v1
	ds_write2_b32 v4, v132, v133 offset1:1
	v_add_u32_e32 v4, 0x38e0, v1
	s_waitcnt vmcnt(1)
	ds_write2_b32 v4, v134, v135 offset1:1
	v_add_u32_e32 v4, 0x38e8, v1
	ds_write2_b32 v4, v136, v137 offset1:1
	v_add_u32_e32 v4, 0x3cf0, v1
	s_waitcnt vmcnt(0)
	ds_write2_b32 v4, v138, v139 offset1:1
	v_add_u32_e32 v4, 0x3cf8, v1
	ds_write2_b32 v4, v140, v141 offset1:1
	s_waitcnt lgkmcnt(0)
	ds_read2_b32 v[82:83], v33 offset0:65 offset1:73
	ds_read2_b32 v[84:85], v33 offset1:8
	ds_read2_b32 v[86:87], v33 offset0:130 offset1:138
	ds_read2_b32 v[88:89], v33 offset0:195 offset1:203
	ds_read2_b32 v[90:91], v77 offset0:4 offset1:12
	ds_read2_b32 v[92:93], v77 offset0:69 offset1:77
	ds_read2_b32 v[94:95], v77 offset0:134 offset1:142
	ds_read2_b32 v[96:97], v77 offset0:199 offset1:207
	v_lshlrev_b32_e32 v4, 1, v32
	v_lshl_add_u64 v[98:99], s[10:11], 0, v[4:5]
	s_waitcnt lgkmcnt(6)
	v_cvt_pk_bf16_f32 v78, v84, v82
	s_waitcnt lgkmcnt(4)
	v_cvt_pk_bf16_f32 v79, v86, v88
	s_waitcnt lgkmcnt(2)
	v_cvt_pk_bf16_f32 v80, v90, v92
	s_waitcnt lgkmcnt(0)
	v_cvt_pk_bf16_f32 v81, v94, v96
	v_lshl_add_u64 v[100:101], v[98:99], 0, v[34:35]
	global_store_dwordx4 v[100:101], v[78:81], off nt
	s_nop 1
	v_cvt_pk_bf16_f32 v78, v85, v83
	v_cvt_pk_bf16_f32 v79, v87, v89
	v_cvt_pk_bf16_f32 v80, v91, v93
	v_cvt_pk_bf16_f32 v81, v95, v97
	ds_read2_b32 v[84:85], v33 offset0:81 offset1:89
	ds_read2_b32 v[86:87], v33 offset0:16 offset1:24
	ds_read2_b32 v[88:89], v33 offset0:146 offset1:154
	ds_read2_b32 v[90:91], v33 offset0:211 offset1:219
	ds_read2_b32 v[92:93], v77 offset0:20 offset1:28
	ds_read2_b32 v[94:95], v77 offset0:85 offset1:93
	ds_read2_b32 v[96:97], v77 offset0:150 offset1:158
	ds_read2_b32 v[100:101], v77 offset0:215 offset1:223
	v_lshl_add_u64 v[82:83], v[98:99], 0, v[36:37]
	global_store_dwordx4 v[82:83], v[78:81], off nt
	v_lshl_add_u64 v[82:83], v[98:99], 0, v[38:39]
	s_waitcnt lgkmcnt(6)
	v_cvt_pk_bf16_f32 v78, v86, v84
	s_waitcnt lgkmcnt(4)
	v_cvt_pk_bf16_f32 v79, v88, v90
	s_waitcnt lgkmcnt(2)
	v_cvt_pk_bf16_f32 v80, v92, v94
	s_waitcnt lgkmcnt(0)
	v_cvt_pk_bf16_f32 v81, v96, v100
	global_store_dwordx4 v[82:83], v[78:81], off nt
	v_lshl_add_u64 v[82:83], v[98:99], 0, v[46:47]
	s_nop 0
	v_cvt_pk_bf16_f32 v78, v87, v85
	v_cvt_pk_bf16_f32 v79, v89, v91
	v_cvt_pk_bf16_f32 v80, v93, v95
	v_cvt_pk_bf16_f32 v81, v97, v101
	ds_read2_b32 v[84:85], v33 offset0:32 offset1:40
	ds_read2_b32 v[86:87], v33 offset0:97 offset1:105
	ds_read2_b32 v[88:89], v33 offset0:162 offset1:170
	ds_read2_b32 v[90:91], v33 offset0:227 offset1:235
	ds_read2_b32 v[92:93], v77 offset0:36 offset1:44
	ds_read2_b32 v[94:95], v77 offset0:101 offset1:109
	ds_read2_b32 v[96:97], v77 offset0:166 offset1:174
	ds_read2_b32 v[100:101], v77 offset0:231 offset1:239
	global_store_dwordx4 v[82:83], v[78:81], off nt
	v_lshl_add_u64 v[82:83], v[98:99], 0, v[50:51]
	s_waitcnt lgkmcnt(6)
	v_cvt_pk_bf16_f32 v78, v84, v86
	s_waitcnt lgkmcnt(4)
	v_cvt_pk_bf16_f32 v79, v88, v90
	s_waitcnt lgkmcnt(2)
	v_cvt_pk_bf16_f32 v80, v92, v94
	s_waitcnt lgkmcnt(0)
	v_cvt_pk_bf16_f32 v81, v96, v100
	global_store_dwordx4 v[82:83], v[78:81], off nt
	v_lshl_add_u64 v[82:83], v[98:99], 0, v[54:55]
	s_nop 0
	v_cvt_pk_bf16_f32 v78, v85, v87
	v_cvt_pk_bf16_f32 v79, v89, v91
	v_cvt_pk_bf16_f32 v80, v93, v95
	v_cvt_pk_bf16_f32 v81, v97, v101
	ds_read2_b32 v[84:85], v33 offset0:48 offset1:56
	ds_read2_b32 v[86:87], v33 offset0:113 offset1:121
	ds_read2_b32 v[88:89], v33 offset0:178 offset1:186
	ds_read2_b32 v[90:91], v33 offset0:243 offset1:251
	ds_read2_b32 v[92:93], v77 offset0:52 offset1:60
	ds_read2_b32 v[94:95], v77 offset0:117 offset1:125
	ds_read2_b32 v[96:97], v77 offset0:182 offset1:190
	ds_read2_b32 v[100:101], v77 offset0:247 offset1:255
	global_store_dwordx4 v[82:83], v[78:81], off nt
	v_lshl_add_u64 v[82:83], v[98:99], 0, v[58:59]
	s_waitcnt lgkmcnt(6)
	v_cvt_pk_bf16_f32 v78, v84, v86
	s_waitcnt lgkmcnt(4)
	v_cvt_pk_bf16_f32 v79, v88, v90
	s_waitcnt lgkmcnt(2)
	v_cvt_pk_bf16_f32 v80, v92, v94
	s_waitcnt lgkmcnt(0)
	v_cvt_pk_bf16_f32 v81, v96, v100
	global_store_dwordx4 v[82:83], v[78:81], off nt
	v_lshl_add_u64 v[82:83], v[98:99], 0, v[62:63]
	s_nop 0
	v_cvt_pk_bf16_f32 v78, v85, v87
	v_cvt_pk_bf16_f32 v79, v89, v91
	v_cvt_pk_bf16_f32 v80, v93, v95
	v_cvt_pk_bf16_f32 v81, v97, v101
	global_store_dwordx4 v[82:83], v[78:81], off nt
	s_waitcnt lgkmcnt(0)

.LBB0_62:
	s_andn2_b64 vcc, exec, s[10:11]
	s_cbranch_vccnz .LBB0_64
	s_and_b32 s0, s9, 0x1fc0
	s_addk_i32 s0, 0xe800
	v_readlane_b32 s56, v234, 7
	s_and_b32 s12, s5, 0x3c0
	s_lshl_b64 s[10:11], s[0:1], 12
	v_readlane_b32 s60, v234, 11
	v_readlane_b32 s61, v234, 12
	s_add_u32 s10, s60, s10
	s_addc_u32 s11, s61, s11
	s_lshl_b32 s13, s12, 2
	s_add_u32 s10, s10, s13
	s_addc_u32 s11, s11, 0
	v_lshl_add_u64 v[78:79], s[10:11], 0, v[66:67]
	v_lshlrev_b32_e32 v4, 2, v2
	v_lshl_add_u64 v[138:139], v[78:79], 0, v[4:5]
	v_add_co_u32_e32 v82, vcc, s21, v138
	v_add_u32_e32 v4, 0x410, v1
	s_nop 0
	v_addc_co_u32_e32 v83, vcc, 0, v139, vcc
	v_add_co_u32_e32 v86, vcc, s24, v138
	global_load_dwordx4 v[78:81], v[138:139], off nt
	s_nop 0
	global_load_dwordx4 v[82:85], v[82:83], off nt
	v_addc_co_u32_e32 v87, vcc, 0, v139, vcc
	v_add_co_u32_e32 v90, vcc, s25, v138
	s_lshl_b32 s10, s12, 12
	s_nop 0
	v_addc_co_u32_e32 v91, vcc, 0, v139, vcc
	global_load_dwordx4 v[86:89], v[86:87], off nt
	s_nop 0
	global_load_dwordx4 v[90:93], v[90:91], off nt
	v_add_co_u32_e32 v94, vcc, s26, v138
	v_readlane_b32 s11, v234, 53
	s_nop 0
	v_addc_co_u32_e32 v95, vcc, 0, v139, vcc
	v_add_co_u32_e32 v98, vcc, s27, v138
	v_add_u32_e32 v77, 0x400, v33
	s_nop 0
	v_addc_co_u32_e32 v99, vcc, 0, v139, vcc
	global_load_dwordx4 v[94:97], v[94:95], off nt
	s_nop 0
	global_load_dwordx4 v[98:101], v[98:99], off nt
	v_add_co_u32_e32 v102, vcc, s28, v138
	s_add_u32 s12, s11, s10
	s_nop 0
	v_addc_co_u32_e32 v103, vcc, 0, v139, vcc
	v_add_co_u32_e32 v106, vcc, s29, v138
	s_addc_u32 s13, s89, 0
	s_nop 0
	v_addc_co_u32_e32 v107, vcc, 0, v139, vcc
	global_load_dwordx4 v[102:105], v[102:103], off nt
	s_nop 0
	global_load_dwordx4 v[106:109], v[106:107], off nt
	v_add_co_u32_e32 v110, vcc, s30, v138
	s_lshl_b64 s[10:11], s[0:1], 1
	s_nop 0
	v_addc_co_u32_e32 v111, vcc, 0, v139, vcc
	v_add_co_u32_e32 v114, vcc, s31, v138
	s_add_u32 s10, s12, s10
	s_nop 0
	v_addc_co_u32_e32 v115, vcc, 0, v139, vcc
	global_load_dwordx4 v[110:113], v[110:111], off nt
	s_nop 0
	global_load_dwordx4 v[114:117], v[114:115], off nt
	v_add_co_u32_e32 v118, vcc, s34, v138
	s_addc_u32 s11, s13, s11
	s_nop 0
	v_addc_co_u32_e32 v119, vcc, 0, v139, vcc
	v_add_co_u32_e32 v122, vcc, s35, v138
	v_readlane_b32 s57, v234, 8
	s_nop 0
	v_addc_co_u32_e32 v123, vcc, 0, v139, vcc
	global_load_dwordx4 v[118:121], v[118:119], off nt
	s_nop 0
	global_load_dwordx4 v[122:125], v[122:123], off nt
	v_add_co_u32_e32 v126, vcc, s36, v138
	v_readlane_b32 s58, v234, 9
	s_nop 0
	v_addc_co_u32_e32 v127, vcc, 0, v139, vcc
	global_load_dwordx4 v[126:129], v[126:127], off nt
	v_add_co_u32_e32 v130, vcc, s37, v138
	v_readlane_b32 s59, v234, 10
	s_nop 0
	v_addc_co_u32_e32 v131, vcc, 0, v139, vcc
	global_load_dwordx4 v[130:133], v[130:131], off nt
	v_add_co_u32_e32 v134, vcc, s38, v138
	v_readlane_b32 s62, v234, 13
	s_nop 0
	v_addc_co_u32_e32 v135, vcc, 0, v139, vcc
	global_load_dwordx4 v[134:137], v[134:135], off nt
	v_add_co_u32_e32 v138, vcc, s39, v138
	v_readlane_b32 s63, v234, 14
	s_nop 0
	v_addc_co_u32_e32 v139, vcc, 0, v139, vcc
	global_load_dwordx4 v[138:141], v[138:139], off nt
	s_waitcnt vmcnt(15)
	ds_write2_b32 v1, v78, v79 offset1:1
	ds_write2_b32 v1, v80, v81 offset0:2 offset1:3
	s_waitcnt vmcnt(14)
	ds_write2_b32 v4, v82, v83 offset1:1
	v_add_u32_e32 v4, 0x418, v1
	ds_write2_b32 v4, v84, v85 offset1:1
	v_add_u32_e32 v4, 0x820, v1
	v_readlane_b32 s64, v234, 15
	v_readlane_b32 s65, v234, 16
	v_readlane_b32 s66, v234, 17
	s_waitcnt vmcnt(13)
	ds_write2_b32 v4, v86, v87 offset1:1
	v_add_u32_e32 v4, 0x828, v1
	ds_write2_b32 v4, v88, v89 offset1:1
	v_add_u32_e32 v4, 0xc30, v1
	s_waitcnt vmcnt(12)
	ds_write2_b32 v4, v90, v91 offset1:1
	v_add_u32_e32 v4, 0xc38, v1
	ds_write2_b32 v4, v92, v93 offset1:1
	v_add_u32_e32 v4, 0x1040, v1
	v_readlane_b32 s67, v234, 18
	v_readlane_b32 s68, v234, 19
	v_readlane_b32 s69, v234, 20
	s_waitcnt vmcnt(11)
	ds_write2_b32 v4, v94, v95 offset1:1
	v_add_u32_e32 v4, 0x1048, v1
	ds_write2_b32 v4, v96, v97 offset1:1
	v_add_u32_e32 v4, 0x1450, v1
	s_waitcnt vmcnt(10)
	ds_write2_b32 v4, v98, v99 offset1:1
	v_add_u32_e32 v4, 0x1458, v1
	ds_write2_b32 v4, v100, v101 offset1:1
	v_add_u32_e32 v4, 0x1860, v1
	v_readlane_b32 s70, v234, 21
	v_readlane_b32 s71, v234, 22
	s_waitcnt vmcnt(9)
	ds_write2_b32 v4, v102, v103 offset1:1
	v_add_u32_e32 v4, 0x1868, v1
	ds_write2_b32 v4, v104, v105 offset1:1
	v_add_u32_e32 v4, 0x1c70, v1
	s_waitcnt vmcnt(8)
	ds_write2_b32 v4, v106, v107 offset1:1
	v_add_u32_e32 v4, 0x1c78, v1
	ds_write2_b32 v4, v108, v109 offset1:1
	v_add_u32_e32 v4, 0x2080, v1
	s_waitcnt vmcnt(7)
	ds_write2_b32 v4, v110, v111 offset1:1
	v_add_u32_e32 v4, 0x2088, v1
	ds_write2_b32 v4, v112, v113 offset1:1
	v_add_u32_e32 v4, 0x2490, v1
	s_waitcnt vmcnt(6)
	ds_write2_b32 v4, v114, v115 offset1:1
	v_add_u32_e32 v4, 0x2498, v1
	ds_write2_b32 v4, v116, v117 offset1:1
	v_add_u32_e32 v4, 0x28a0, v1
	s_waitcnt vmcnt(5)
	ds_write2_b32 v4, v118, v119 offset1:1
	v_add_u32_e32 v4, 0x28a8, v1
	ds_write2_b32 v4, v120, v121 offset1:1
	v_add_u32_e32 v4, 0x2cb0, v1
	s_waitcnt vmcnt(4)
	ds_write2_b32 v4, v122, v123 offset1:1
	v_add_u32_e32 v4, 0x2cb8, v1
	ds_write2_b32 v4, v124, v125 offset1:1
	v_add_u32_e32 v4, 0x30c0, v1
	s_waitcnt vmcnt(3)
	ds_write2_b32 v4, v126, v127 offset1:1
	v_add_u32_e32 v4, 0x30c8, v1
	ds_write2_b32 v4, v128, v129 offset1:1
	v_add_u32_e32 v4, 0x34d0, v1
	s_waitcnt vmcnt(2)
	ds_write2_b32 v4, v130, v131 offset1:1
	v_add_u32_e32 v4, 0x34d8, v1
	ds_write2_b32 v4, v132, v133 offset1:1
	v_add_u32_e32 v4, 0x38e0, v1
	s_waitcnt vmcnt(1)
	ds_write2_b32 v4, v134, v135 offset1:1
	v_add_u32_e32 v4, 0x38e8, v1
	ds_write2_b32 v4, v136, v137 offset1:1
	v_add_u32_e32 v4, 0x3cf0, v1
	s_waitcnt vmcnt(0)
	ds_write2_b32 v4, v138, v139 offset1:1
	v_add_u32_e32 v4, 0x3cf8, v1
	ds_write2_b32 v4, v140, v141 offset1:1
	s_waitcnt lgkmcnt(0)
	ds_read2_b32 v[82:83], v33 offset0:65 offset1:73
	ds_read2_b32 v[84:85], v33 offset1:8
	ds_read2_b32 v[86:87], v33 offset0:130 offset1:138
	ds_read2_b32 v[88:89], v33 offset0:195 offset1:203
	ds_read2_b32 v[90:91], v77 offset0:4 offset1:12
	ds_read2_b32 v[92:93], v77 offset0:69 offset1:77
	ds_read2_b32 v[94:95], v77 offset0:134 offset1:142
	ds_read2_b32 v[96:97], v77 offset0:199 offset1:207
	v_lshlrev_b32_e32 v4, 1, v32
	v_lshl_add_u64 v[98:99], s[10:11], 0, v[4:5]
	s_waitcnt lgkmcnt(6)
	v_cvt_pk_bf16_f32 v78, v84, v82
	s_waitcnt lgkmcnt(4)
	v_cvt_pk_bf16_f32 v79, v86, v88
	s_waitcnt lgkmcnt(2)
	v_cvt_pk_bf16_f32 v80, v90, v92
	s_waitcnt lgkmcnt(0)
	v_cvt_pk_bf16_f32 v81, v94, v96
	v_lshl_add_u64 v[100:101], v[98:99], 0, v[40:41]
	global_store_dwordx4 v[100:101], v[78:81], off nt
	s_nop 1
	v_cvt_pk_bf16_f32 v78, v85, v83
	v_cvt_pk_bf16_f32 v79, v87, v89
	v_cvt_pk_bf16_f32 v80, v91, v93
	v_cvt_pk_bf16_f32 v81, v95, v97
	ds_read2_b32 v[84:85], v33 offset0:81 offset1:89
	ds_read2_b32 v[86:87], v33 offset0:16 offset1:24
	ds_read2_b32 v[88:89], v33 offset0:146 offset1:154
	ds_read2_b32 v[90:91], v33 offset0:211 offset1:219
	ds_read2_b32 v[92:93], v77 offset0:20 offset1:28
	ds_read2_b32 v[94:95], v77 offset0:85 offset1:93
	ds_read2_b32 v[96:97], v77 offset0:150 offset1:158
	ds_read2_b32 v[100:101], v77 offset0:215 offset1:223
	v_lshl_add_u64 v[82:83], v[98:99], 0, v[42:43]
	global_store_dwordx4 v[82:83], v[78:81], off nt
	v_lshl_add_u64 v[82:83], v[98:99], 0, v[44:45]
	s_waitcnt lgkmcnt(6)
	v_cvt_pk_bf16_f32 v78, v86, v84
	s_waitcnt lgkmcnt(4)
	v_cvt_pk_bf16_f32 v79, v88, v90
	s_waitcnt lgkmcnt(2)
	v_cvt_pk_bf16_f32 v80, v92, v94
	s_waitcnt lgkmcnt(0)
	v_cvt_pk_bf16_f32 v81, v96, v100
	global_store_dwordx4 v[82:83], v[78:81], off nt
	v_lshl_add_u64 v[82:83], v[98:99], 0, v[48:49]
	s_nop 0
	v_cvt_pk_bf16_f32 v78, v87, v85
	v_cvt_pk_bf16_f32 v79, v89, v91
	v_cvt_pk_bf16_f32 v80, v93, v95
	v_cvt_pk_bf16_f32 v81, v97, v101
	ds_read2_b32 v[84:85], v33 offset0:32 offset1:40
	ds_read2_b32 v[86:87], v33 offset0:97 offset1:105
	ds_read2_b32 v[88:89], v33 offset0:162 offset1:170
	ds_read2_b32 v[90:91], v33 offset0:227 offset1:235
	ds_read2_b32 v[92:93], v77 offset0:36 offset1:44
	ds_read2_b32 v[94:95], v77 offset0:101 offset1:109
	ds_read2_b32 v[96:97], v77 offset0:166 offset1:174
	ds_read2_b32 v[100:101], v77 offset0:231 offset1:239
	global_store_dwordx4 v[82:83], v[78:81], off nt
	v_lshl_add_u64 v[82:83], v[98:99], 0, v[52:53]
	s_waitcnt lgkmcnt(6)
	v_cvt_pk_bf16_f32 v78, v84, v86
	s_waitcnt lgkmcnt(4)
	v_cvt_pk_bf16_f32 v79, v88, v90
	s_waitcnt lgkmcnt(2)
	v_cvt_pk_bf16_f32 v80, v92, v94
	s_waitcnt lgkmcnt(0)
	v_cvt_pk_bf16_f32 v81, v96, v100
	global_store_dwordx4 v[82:83], v[78:81], off nt
	v_lshl_add_u64 v[82:83], v[98:99], 0, v[56:57]
	s_nop 0
	v_cvt_pk_bf16_f32 v78, v85, v87
	v_cvt_pk_bf16_f32 v79, v89, v91
	v_cvt_pk_bf16_f32 v80, v93, v95
	v_cvt_pk_bf16_f32 v81, v97, v101
	ds_read2_b32 v[84:85], v33 offset0:48 offset1:56
	ds_read2_b32 v[86:87], v33 offset0:113 offset1:121
	ds_read2_b32 v[88:89], v33 offset0:178 offset1:186
	ds_read2_b32 v[90:91], v33 offset0:243 offset1:251
	ds_read2_b32 v[92:93], v77 offset0:52 offset1:60
	ds_read2_b32 v[94:95], v77 offset0:117 offset1:125
	ds_read2_b32 v[96:97], v77 offset0:182 offset1:190
	ds_read2_b32 v[100:101], v77 offset0:247 offset1:255
	global_store_dwordx4 v[82:83], v[78:81], off nt
	v_lshl_add_u64 v[82:83], v[98:99], 0, v[60:61]
	s_waitcnt lgkmcnt(6)
	v_cvt_pk_bf16_f32 v78, v84, v86
	s_waitcnt lgkmcnt(4)
	v_cvt_pk_bf16_f32 v79, v88, v90
	s_waitcnt lgkmcnt(2)
	v_cvt_pk_bf16_f32 v80, v92, v94
	s_waitcnt lgkmcnt(0)
	v_cvt_pk_bf16_f32 v81, v96, v100
	global_store_dwordx4 v[82:83], v[78:81], off nt
	v_lshl_add_u64 v[82:83], v[98:99], 0, v[64:65]
	s_nop 0
	v_cvt_pk_bf16_f32 v78, v85, v87
	v_cvt_pk_bf16_f32 v79, v89, v91
	v_cvt_pk_bf16_f32 v80, v93, v95
	v_cvt_pk_bf16_f32 v81, v97, v101
	global_store_dwordx4 v[82:83], v[78:81], off nt
	s_waitcnt lgkmcnt(0)
